# sec 9.3 placement: the 14 GEMM K-loop heads pinned to 64-byte boundaries
# baseline (speedup 1.0000x reference)
; template <class Epi, class Sched>
; __device__ __forceinline__ void gemm_phase(PG8_LAS unsigned char* lds, const Gemm g, const Sched& S, const Epi& E) {
;     ...
;         for (int t = 0; t < nt; t += 2) {
;             const bool last = (t == nt - 2);
;             const char* a1 = cA + (size_t)(t + 1) * kstep;
;             const char* a2 = last ? nA : cA + (size_t)(t + 2) * kstep; const char* b2 = last ? nB : cB + (size_t)(t + 2) * kstep;
;             const char* a3 = a2 + kstep; const char* b3 = b2 + kstep;
;     ...
; #pragma unroll
;         for (int a = 0; a < 2; ++a)
; #pragma unroll
;             for (int b = 0; b < 2; ++b)
; #pragma unroll
;                 for (int m = 0; m < 4; ++m)
; #pragma unroll
;                     for (int n = 0; n < 2; ++n) acc[a][b][m][n] = (f32x4){0.f, 0.f, 0.f, 0.f};
;         cur = nxt; cA = nA; cB = nB; ++ui;
.LBB0_319:
	v_mov_b32_e32 v125, 0
	s_andn2_b64 vcc, exec, s[30:31]
	v_mov_b32_e32 v124, v125
	v_mov_b32_e32 v123, v125
	v_mov_b32_e32 v122, v125
	v_mov_b32_e32 v129, v125
	v_mov_b32_e32 v128, v125
	v_mov_b32_e32 v127, v125
	v_mov_b32_e32 v126, v125
	v_mov_b32_e32 v113, v125
	v_mov_b32_e32 v112, v125
	v_mov_b32_e32 v111, v125
	v_mov_b32_e32 v110, v125
	v_mov_b32_e32 v109, v125
	v_mov_b32_e32 v108, v125
	v_mov_b32_e32 v107, v125
	v_mov_b32_e32 v106, v125
	v_mov_b32_e32 v97, v125
	v_mov_b32_e32 v96, v125
	v_mov_b32_e32 v95, v125
	v_mov_b32_e32 v94, v125
	v_mov_b32_e32 v93, v125
	v_mov_b32_e32 v92, v125
	v_mov_b32_e32 v91, v125
	v_mov_b32_e32 v90, v125
	v_mov_b32_e32 v81, v125
	v_mov_b32_e32 v80, v125
	v_mov_b32_e32 v79, v125
	v_mov_b32_e32 v78, v125
	v_mov_b32_e32 v77, v125
	v_mov_b32_e32 v76, v125
	v_mov_b32_e32 v75, v125
	v_mov_b32_e32 v74, v125
	v_mov_b32_e32 v121, v125
	v_mov_b32_e32 v120, v125
	v_mov_b32_e32 v119, v125
	v_mov_b32_e32 v118, v125
	v_mov_b32_e32 v117, v125
	v_mov_b32_e32 v116, v125
	v_mov_b32_e32 v115, v125
	v_mov_b32_e32 v114, v125
	v_mov_b32_e32 v105, v125
	v_mov_b32_e32 v104, v125
	v_mov_b32_e32 v103, v125
	v_mov_b32_e32 v102, v125
	v_mov_b32_e32 v101, v125
	v_mov_b32_e32 v100, v125
	v_mov_b32_e32 v99, v125
	v_mov_b32_e32 v98, v125
	v_mov_b32_e32 v89, v125
	v_mov_b32_e32 v88, v125
	v_mov_b32_e32 v87, v125
	v_mov_b32_e32 v86, v125
	v_mov_b32_e32 v85, v125
	v_mov_b32_e32 v84, v125
	v_mov_b32_e32 v83, v125
	v_mov_b32_e32 v82, v125
	v_mov_b32_e32 v73, v125
	v_mov_b32_e32 v72, v125
	v_mov_b32_e32 v71, v125
	v_mov_b32_e32 v70, v125
	v_mov_b32_e32 v69, v125
	v_mov_b32_e32 v68, v125
	v_mov_b32_e32 v67, v125
	v_mov_b32_e32 v66, v125
	v_mov_b32_e32 v65, v125
	v_mov_b32_e32 v64, v125
	v_mov_b32_e32 v63, v125
	v_mov_b32_e32 v62, v125
	v_mov_b32_e32 v61, v125
	v_mov_b32_e32 v60, v125
	v_mov_b32_e32 v59, v125
	v_mov_b32_e32 v58, v125
	v_mov_b32_e32 v49, v125
	v_mov_b32_e32 v48, v125
	v_mov_b32_e32 v47, v125
	v_mov_b32_e32 v46, v125
	v_mov_b32_e32 v45, v125
	v_mov_b32_e32 v44, v125
	v_mov_b32_e32 v43, v125
	v_mov_b32_e32 v42, v125
	v_mov_b32_e32 v33, v125
	v_mov_b32_e32 v32, v125
	v_mov_b32_e32 v31, v125
	v_mov_b32_e32 v30, v125
	v_mov_b32_e32 v29, v125
	v_mov_b32_e32 v28, v125
	v_mov_b32_e32 v27, v125
	v_mov_b32_e32 v26, v125
	v_mov_b32_e32 v17, v125
	v_mov_b32_e32 v16, v125
	v_mov_b32_e32 v15, v125
	v_mov_b32_e32 v14, v125
	v_mov_b32_e32 v13, v125
	v_mov_b32_e32 v12, v125
	v_mov_b32_e32 v11, v125
	v_mov_b32_e32 v10, v125
	v_mov_b32_e32 v57, v125
	v_mov_b32_e32 v56, v125
	v_mov_b32_e32 v55, v125
	v_mov_b32_e32 v54, v125
	v_mov_b32_e32 v53, v125
	v_mov_b32_e32 v52, v125
	v_mov_b32_e32 v51, v125
	v_mov_b32_e32 v50, v125
	v_mov_b32_e32 v41, v125
	v_mov_b32_e32 v40, v125
	v_mov_b32_e32 v39, v125
	v_mov_b32_e32 v38, v125
	v_mov_b32_e32 v37, v125
	v_mov_b32_e32 v36, v125
	v_mov_b32_e32 v35, v125
	v_mov_b32_e32 v34, v125
	v_mov_b32_e32 v25, v125
	v_mov_b32_e32 v24, v125
	v_mov_b32_e32 v23, v125
	v_mov_b32_e32 v22, v125
	v_mov_b32_e32 v21, v125
	v_mov_b32_e32 v20, v125
	v_mov_b32_e32 v19, v125
	v_mov_b32_e32 v18, v125
	v_mov_b32_e32 v9, v125
	v_mov_b32_e32 v8, v125
	v_mov_b32_e32 v7, v125
	v_mov_b32_e32 v6, v125
	v_mov_b32_e32 v5, v125
	v_mov_b32_e32 v4, v125
	v_mov_b32_e32 v3, v125
	v_mov_b32_e32 v2, v125
	s_cbranch_vccnz .LBB0_323
	s_add_u32 s42, s42, 0x80
	s_addc_u32 s43, s43, 0
	s_add_u32 s70, s44, 0x100
	v_mov_b32_e32 v2, 0
	s_addc_u32 s71, s45, 0
	s_mov_b32 s44, 0
	v_mov_b32_e32 v3, v2
	v_mov_b32_e32 v4, v2
	v_mov_b32_e32 v5, v2
	v_mov_b32_e32 v6, v2
	v_mov_b32_e32 v7, v2
	v_mov_b32_e32 v8, v2
	v_mov_b32_e32 v9, v2
	v_mov_b32_e32 v18, v2
	v_mov_b32_e32 v19, v2
	v_mov_b32_e32 v20, v2
	v_mov_b32_e32 v21, v2
	v_mov_b32_e32 v22, v2
	v_mov_b32_e32 v23, v2
	v_mov_b32_e32 v24, v2
	v_mov_b32_e32 v25, v2
	v_mov_b32_e32 v34, v2
	v_mov_b32_e32 v35, v2
	v_mov_b32_e32 v36, v2
	v_mov_b32_e32 v37, v2
	v_mov_b32_e32 v38, v2
	v_mov_b32_e32 v39, v2
	v_mov_b32_e32 v40, v2
	v_mov_b32_e32 v41, v2
	v_mov_b32_e32 v50, v2
	v_mov_b32_e32 v51, v2
	v_mov_b32_e32 v52, v2
	v_mov_b32_e32 v53, v2
	v_mov_b32_e32 v54, v2
	v_mov_b32_e32 v55, v2
	v_mov_b32_e32 v56, v2
	v_mov_b32_e32 v57, v2
	v_mov_b32_e32 v10, v2
	v_mov_b32_e32 v11, v2
	v_mov_b32_e32 v12, v2
	v_mov_b32_e32 v13, v2
	v_mov_b32_e32 v14, v2
	v_mov_b32_e32 v15, v2
	v_mov_b32_e32 v16, v2
	v_mov_b32_e32 v17, v2
	v_mov_b32_e32 v26, v2
	v_mov_b32_e32 v27, v2
	v_mov_b32_e32 v28, v2
	v_mov_b32_e32 v29, v2
	v_mov_b32_e32 v30, v2
	v_mov_b32_e32 v31, v2
	v_mov_b32_e32 v32, v2
	v_mov_b32_e32 v33, v2
	v_mov_b32_e32 v42, v2
	v_mov_b32_e32 v43, v2
	v_mov_b32_e32 v44, v2
	v_mov_b32_e32 v45, v2
	v_mov_b32_e32 v46, v2
	v_mov_b32_e32 v47, v2
	v_mov_b32_e32 v48, v2
	v_mov_b32_e32 v49, v2
	v_mov_b32_e32 v58, v2
	v_mov_b32_e32 v59, v2
	v_mov_b32_e32 v60, v2
	v_mov_b32_e32 v61, v2
	v_mov_b32_e32 v62, v2
	v_mov_b32_e32 v63, v2
	v_mov_b32_e32 v64, v2
	v_mov_b32_e32 v65, v2
	v_mov_b32_e32 v66, v2
	v_mov_b32_e32 v67, v2
	v_mov_b32_e32 v68, v2
	v_mov_b32_e32 v69, v2
	v_mov_b32_e32 v70, v2
	v_mov_b32_e32 v71, v2
	v_mov_b32_e32 v72, v2
	v_mov_b32_e32 v73, v2
	v_mov_b32_e32 v82, v2
	v_mov_b32_e32 v83, v2
	v_mov_b32_e32 v84, v2
	v_mov_b32_e32 v85, v2
	v_mov_b32_e32 v86, v2
	v_mov_b32_e32 v87, v2
	v_mov_b32_e32 v88, v2
	v_mov_b32_e32 v89, v2
	v_mov_b32_e32 v98, v2
	v_mov_b32_e32 v99, v2
	v_mov_b32_e32 v100, v2
	v_mov_b32_e32 v101, v2
	v_mov_b32_e32 v102, v2
	v_mov_b32_e32 v103, v2
	v_mov_b32_e32 v104, v2
	v_mov_b32_e32 v105, v2
	v_mov_b32_e32 v114, v2
	v_mov_b32_e32 v115, v2
	v_mov_b32_e32 v116, v2
	v_mov_b32_e32 v117, v2
	v_mov_b32_e32 v118, v2
	v_mov_b32_e32 v119, v2
	v_mov_b32_e32 v120, v2
	v_mov_b32_e32 v121, v2
	v_mov_b32_e32 v74, v2
	v_mov_b32_e32 v75, v2
	v_mov_b32_e32 v76, v2
	v_mov_b32_e32 v77, v2
	v_mov_b32_e32 v78, v2
	v_mov_b32_e32 v79, v2
	v_mov_b32_e32 v80, v2
	v_mov_b32_e32 v81, v2
	v_mov_b32_e32 v90, v2
	v_mov_b32_e32 v91, v2
	v_mov_b32_e32 v92, v2
	v_mov_b32_e32 v93, v2
	v_mov_b32_e32 v94, v2
	v_mov_b32_e32 v95, v2
	v_mov_b32_e32 v96, v2
	v_mov_b32_e32 v97, v2
	v_mov_b32_e32 v106, v2
	v_mov_b32_e32 v107, v2
	v_mov_b32_e32 v108, v2
	v_mov_b32_e32 v109, v2
	v_mov_b32_e32 v110, v2
	v_mov_b32_e32 v111, v2
	v_mov_b32_e32 v112, v2
	v_mov_b32_e32 v113, v2
	v_mov_b32_e32 v126, v2
	v_mov_b32_e32 v127, v2
	v_mov_b32_e32 v128, v2
	v_mov_b32_e32 v129, v2
	v_mov_b32_e32 v122, v2
	v_mov_b32_e32 v123, v2
	v_mov_b32_e32 v124, v2
	v_mov_b32_e32 v125, v2
	.p2align	6

; template <class Epi, class Sched>
; __device__ __forceinline__ void gemm_phase(PG8_LAS unsigned char* lds, const Gemm g, const Sched& S, const Epi& E) {
;     ...
;         for (int t = 0; t < nt; t += 2) {
;             const bool last = (t == nt - 2);
;             const char* a1 = cA + (size_t)(t + 1) * kstep;
;             const char* a2 = last ? nA : cA + (size_t)(t + 2) * kstep; const char* b2 = last ? nB : cB + (size_t)(t + 2) * kstep;
;             const char* a3 = a2 + kstep; const char* b3 = b2 + kstep;
;     ...
; #pragma unroll
;         for (int a = 0; a < 2; ++a)
; #pragma unroll
;             for (int b = 0; b < 2; ++b)
; #pragma unroll
;                 for (int m = 0; m < 4; ++m)
; #pragma unroll
;                     for (int n = 0; n < 2; ++n) acc[a][b][m][n] = (f32x4){0.f, 0.f, 0.f, 0.f};
;         cur = nxt; cA = nA; cB = nB; ++ui;
.LBB0_509:
	v_mov_b32_e32 v125, 0
	s_andn2_b64 vcc, exec, s[30:31]
	v_mov_b32_e32 v124, v125
	v_mov_b32_e32 v123, v125
	v_mov_b32_e32 v122, v125
	v_mov_b32_e32 v129, v125
	v_mov_b32_e32 v128, v125
	v_mov_b32_e32 v127, v125
	v_mov_b32_e32 v126, v125
	v_mov_b32_e32 v113, v125
	v_mov_b32_e32 v112, v125
	v_mov_b32_e32 v111, v125
	v_mov_b32_e32 v110, v125
	v_mov_b32_e32 v109, v125
	v_mov_b32_e32 v108, v125
	v_mov_b32_e32 v107, v125
	v_mov_b32_e32 v106, v125
	v_mov_b32_e32 v97, v125
	v_mov_b32_e32 v96, v125
	v_mov_b32_e32 v95, v125
	v_mov_b32_e32 v94, v125
	v_mov_b32_e32 v93, v125
	v_mov_b32_e32 v92, v125
	v_mov_b32_e32 v91, v125
	v_mov_b32_e32 v90, v125
	v_mov_b32_e32 v81, v125
	v_mov_b32_e32 v80, v125
	v_mov_b32_e32 v79, v125
	v_mov_b32_e32 v78, v125
	v_mov_b32_e32 v77, v125
	v_mov_b32_e32 v76, v125
	v_mov_b32_e32 v75, v125
	v_mov_b32_e32 v74, v125
	v_mov_b32_e32 v121, v125
	v_mov_b32_e32 v120, v125
	v_mov_b32_e32 v119, v125
	v_mov_b32_e32 v118, v125
	v_mov_b32_e32 v117, v125
	v_mov_b32_e32 v116, v125
	v_mov_b32_e32 v115, v125
	v_mov_b32_e32 v114, v125
	v_mov_b32_e32 v105, v125
	v_mov_b32_e32 v104, v125
	v_mov_b32_e32 v103, v125
	v_mov_b32_e32 v102, v125
	v_mov_b32_e32 v101, v125
	v_mov_b32_e32 v100, v125
	v_mov_b32_e32 v99, v125
	v_mov_b32_e32 v98, v125
	v_mov_b32_e32 v89, v125
	v_mov_b32_e32 v88, v125
	v_mov_b32_e32 v87, v125
	v_mov_b32_e32 v86, v125
	v_mov_b32_e32 v85, v125
	v_mov_b32_e32 v84, v125
	v_mov_b32_e32 v83, v125
	v_mov_b32_e32 v82, v125
	v_mov_b32_e32 v73, v125
	v_mov_b32_e32 v72, v125
	v_mov_b32_e32 v71, v125
	v_mov_b32_e32 v70, v125
	v_mov_b32_e32 v69, v125
	v_mov_b32_e32 v68, v125
	v_mov_b32_e32 v67, v125
	v_mov_b32_e32 v66, v125
	v_mov_b32_e32 v65, v125
	v_mov_b32_e32 v64, v125
	v_mov_b32_e32 v63, v125
	v_mov_b32_e32 v62, v125
	v_mov_b32_e32 v61, v125
	v_mov_b32_e32 v60, v125
	v_mov_b32_e32 v59, v125
	v_mov_b32_e32 v58, v125
	v_mov_b32_e32 v49, v125
	v_mov_b32_e32 v48, v125
	v_mov_b32_e32 v47, v125
	v_mov_b32_e32 v46, v125
	v_mov_b32_e32 v45, v125
	v_mov_b32_e32 v44, v125
	v_mov_b32_e32 v43, v125
	v_mov_b32_e32 v42, v125
	v_mov_b32_e32 v33, v125
	v_mov_b32_e32 v32, v125
	v_mov_b32_e32 v31, v125
	v_mov_b32_e32 v30, v125
	v_mov_b32_e32 v29, v125
	v_mov_b32_e32 v28, v125
	v_mov_b32_e32 v27, v125
	v_mov_b32_e32 v26, v125
	v_mov_b32_e32 v17, v125
	v_mov_b32_e32 v16, v125
	v_mov_b32_e32 v15, v125
	v_mov_b32_e32 v14, v125
	v_mov_b32_e32 v13, v125
	v_mov_b32_e32 v12, v125
	v_mov_b32_e32 v11, v125
	v_mov_b32_e32 v10, v125
	v_mov_b32_e32 v57, v125
	v_mov_b32_e32 v56, v125
	v_mov_b32_e32 v55, v125
	v_mov_b32_e32 v54, v125
	v_mov_b32_e32 v53, v125
	v_mov_b32_e32 v52, v125
	v_mov_b32_e32 v51, v125
	v_mov_b32_e32 v50, v125
	v_mov_b32_e32 v41, v125
	v_mov_b32_e32 v40, v125
	v_mov_b32_e32 v39, v125
	v_mov_b32_e32 v38, v125
	v_mov_b32_e32 v37, v125
	v_mov_b32_e32 v36, v125
	v_mov_b32_e32 v35, v125
	v_mov_b32_e32 v34, v125
	v_mov_b32_e32 v25, v125
	v_mov_b32_e32 v24, v125
	v_mov_b32_e32 v23, v125
	v_mov_b32_e32 v22, v125
	v_mov_b32_e32 v21, v125
	v_mov_b32_e32 v20, v125
	v_mov_b32_e32 v19, v125
	v_mov_b32_e32 v18, v125
	v_mov_b32_e32 v9, v125
	v_mov_b32_e32 v8, v125
	v_mov_b32_e32 v7, v125
	v_mov_b32_e32 v6, v125
	v_mov_b32_e32 v5, v125
	v_mov_b32_e32 v4, v125
	v_mov_b32_e32 v3, v125
	v_mov_b32_e32 v2, v125
	s_cbranch_vccnz .LBB0_512
	s_add_u32 s42, s42, 0x80
	s_addc_u32 s43, s43, 0
	s_add_u32 s72, s44, 0x100
	v_mov_b32_e32 v2, 0
	s_addc_u32 s73, s45, 0
	s_mov_b32 s44, 0
	v_mov_b32_e32 v3, v2
	v_mov_b32_e32 v4, v2
	v_mov_b32_e32 v5, v2
	v_mov_b32_e32 v6, v2
	v_mov_b32_e32 v7, v2
	v_mov_b32_e32 v8, v2
	v_mov_b32_e32 v9, v2
	v_mov_b32_e32 v18, v2
	v_mov_b32_e32 v19, v2
	v_mov_b32_e32 v20, v2
	v_mov_b32_e32 v21, v2
	v_mov_b32_e32 v22, v2
	v_mov_b32_e32 v23, v2
	v_mov_b32_e32 v24, v2
	v_mov_b32_e32 v25, v2
	v_mov_b32_e32 v34, v2
	v_mov_b32_e32 v35, v2
	v_mov_b32_e32 v36, v2
	v_mov_b32_e32 v37, v2
	v_mov_b32_e32 v38, v2
	v_mov_b32_e32 v39, v2
	v_mov_b32_e32 v40, v2
	v_mov_b32_e32 v41, v2
	v_mov_b32_e32 v50, v2
	v_mov_b32_e32 v51, v2
	v_mov_b32_e32 v52, v2
	v_mov_b32_e32 v53, v2
	v_mov_b32_e32 v54, v2
	v_mov_b32_e32 v55, v2
	v_mov_b32_e32 v56, v2
	v_mov_b32_e32 v57, v2
	v_mov_b32_e32 v10, v2
	v_mov_b32_e32 v11, v2
	v_mov_b32_e32 v12, v2
	v_mov_b32_e32 v13, v2
	v_mov_b32_e32 v14, v2
	v_mov_b32_e32 v15, v2
	v_mov_b32_e32 v16, v2
	v_mov_b32_e32 v17, v2
	v_mov_b32_e32 v26, v2
	v_mov_b32_e32 v27, v2
	v_mov_b32_e32 v28, v2
	v_mov_b32_e32 v29, v2
	v_mov_b32_e32 v30, v2
	v_mov_b32_e32 v31, v2
	v_mov_b32_e32 v32, v2
	v_mov_b32_e32 v33, v2
	v_mov_b32_e32 v42, v2
	v_mov_b32_e32 v43, v2
	v_mov_b32_e32 v44, v2
	v_mov_b32_e32 v45, v2
	v_mov_b32_e32 v46, v2
	v_mov_b32_e32 v47, v2
	v_mov_b32_e32 v48, v2
	v_mov_b32_e32 v49, v2
	v_mov_b32_e32 v58, v2
	v_mov_b32_e32 v59, v2
	v_mov_b32_e32 v60, v2
	v_mov_b32_e32 v61, v2
	v_mov_b32_e32 v62, v2
	v_mov_b32_e32 v63, v2
	v_mov_b32_e32 v64, v2
	v_mov_b32_e32 v65, v2
	v_mov_b32_e32 v66, v2
	v_mov_b32_e32 v67, v2
	v_mov_b32_e32 v68, v2
	v_mov_b32_e32 v69, v2
	v_mov_b32_e32 v70, v2
	v_mov_b32_e32 v71, v2
	v_mov_b32_e32 v72, v2
	v_mov_b32_e32 v73, v2
	v_mov_b32_e32 v82, v2
	v_mov_b32_e32 v83, v2
	v_mov_b32_e32 v84, v2
	v_mov_b32_e32 v85, v2
	v_mov_b32_e32 v86, v2
	v_mov_b32_e32 v87, v2
	v_mov_b32_e32 v88, v2
	v_mov_b32_e32 v89, v2
	v_mov_b32_e32 v98, v2
	v_mov_b32_e32 v99, v2
	v_mov_b32_e32 v100, v2
	v_mov_b32_e32 v101, v2
	v_mov_b32_e32 v102, v2
	v_mov_b32_e32 v103, v2
	v_mov_b32_e32 v104, v2
	v_mov_b32_e32 v105, v2
	v_mov_b32_e32 v114, v2
	v_mov_b32_e32 v115, v2
	v_mov_b32_e32 v116, v2
	v_mov_b32_e32 v117, v2
	v_mov_b32_e32 v118, v2
	v_mov_b32_e32 v119, v2
	v_mov_b32_e32 v120, v2
	v_mov_b32_e32 v121, v2
	v_mov_b32_e32 v74, v2
	v_mov_b32_e32 v75, v2
	v_mov_b32_e32 v76, v2
	v_mov_b32_e32 v77, v2
	v_mov_b32_e32 v78, v2
	v_mov_b32_e32 v79, v2
	v_mov_b32_e32 v80, v2
	v_mov_b32_e32 v81, v2
	v_mov_b32_e32 v90, v2
	v_mov_b32_e32 v91, v2
	v_mov_b32_e32 v92, v2
	v_mov_b32_e32 v93, v2
	v_mov_b32_e32 v94, v2
	v_mov_b32_e32 v95, v2
	v_mov_b32_e32 v96, v2
	v_mov_b32_e32 v97, v2
	v_mov_b32_e32 v106, v2
	v_mov_b32_e32 v107, v2
	v_mov_b32_e32 v108, v2
	v_mov_b32_e32 v109, v2
	v_mov_b32_e32 v110, v2
	v_mov_b32_e32 v111, v2
	v_mov_b32_e32 v112, v2
	v_mov_b32_e32 v113, v2
	v_mov_b32_e32 v126, v2
	v_mov_b32_e32 v127, v2
	v_mov_b32_e32 v128, v2
	v_mov_b32_e32 v129, v2
	v_mov_b32_e32 v122, v2
	v_mov_b32_e32 v123, v2
	v_mov_b32_e32 v124, v2
	v_mov_b32_e32 v125, v2
	.p2align	6

; template <class Epi, class Sched>
; __device__ __forceinline__ void gemm_phase(PG8_LAS unsigned char* lds, const Gemm g, const Sched& S, const Epi& E) {
;     ...
;         for (int t = 0; t < nt; t += 2) {
;             const bool last = (t == nt - 2);
;             const char* a1 = cA + (size_t)(t + 1) * kstep;
;             const char* a2 = last ? nA : cA + (size_t)(t + 2) * kstep; const char* b2 = last ? nB : cB + (size_t)(t + 2) * kstep;
;             const char* a3 = a2 + kstep; const char* b3 = b2 + kstep;
;     ...
; #pragma unroll
;         for (int a = 0; a < 2; ++a)
; #pragma unroll
;             for (int b = 0; b < 2; ++b)
; #pragma unroll
;                 for (int m = 0; m < 4; ++m)
; #pragma unroll
;                     for (int n = 0; n < 2; ++n) acc[a][b][m][n] = (f32x4){0.f, 0.f, 0.f, 0.f};
;         cur = nxt; cA = nA; cB = nB; ++ui;
.LBB0_534:
	v_mov_b32_e32 v125, 0
	s_andn2_b64 vcc, exec, s[38:39]
	v_mov_b32_e32 v124, v125
	v_mov_b32_e32 v123, v125
	v_mov_b32_e32 v122, v125
	v_mov_b32_e32 v129, v125
	v_mov_b32_e32 v128, v125
	v_mov_b32_e32 v127, v125
	v_mov_b32_e32 v126, v125
	v_mov_b32_e32 v113, v125
	v_mov_b32_e32 v112, v125
	v_mov_b32_e32 v111, v125
	v_mov_b32_e32 v110, v125
	v_mov_b32_e32 v109, v125
	v_mov_b32_e32 v108, v125
	v_mov_b32_e32 v107, v125
	v_mov_b32_e32 v106, v125
	v_mov_b32_e32 v97, v125
	v_mov_b32_e32 v96, v125
	v_mov_b32_e32 v95, v125
	v_mov_b32_e32 v94, v125
	v_mov_b32_e32 v93, v125
	v_mov_b32_e32 v92, v125
	v_mov_b32_e32 v91, v125
	v_mov_b32_e32 v90, v125
	v_mov_b32_e32 v81, v125
	v_mov_b32_e32 v80, v125
	v_mov_b32_e32 v79, v125
	v_mov_b32_e32 v78, v125
	v_mov_b32_e32 v77, v125
	v_mov_b32_e32 v76, v125
	v_mov_b32_e32 v75, v125
	v_mov_b32_e32 v74, v125
	v_mov_b32_e32 v121, v125
	v_mov_b32_e32 v120, v125
	v_mov_b32_e32 v119, v125
	v_mov_b32_e32 v118, v125
	v_mov_b32_e32 v117, v125
	v_mov_b32_e32 v116, v125
	v_mov_b32_e32 v115, v125
	v_mov_b32_e32 v114, v125
	v_mov_b32_e32 v105, v125
	v_mov_b32_e32 v104, v125
	v_mov_b32_e32 v103, v125
	v_mov_b32_e32 v102, v125
	v_mov_b32_e32 v101, v125
	v_mov_b32_e32 v100, v125
	v_mov_b32_e32 v99, v125
	v_mov_b32_e32 v98, v125
	v_mov_b32_e32 v89, v125
	v_mov_b32_e32 v88, v125
	v_mov_b32_e32 v87, v125
	v_mov_b32_e32 v86, v125
	v_mov_b32_e32 v85, v125
	v_mov_b32_e32 v84, v125
	v_mov_b32_e32 v83, v125
	v_mov_b32_e32 v82, v125
	v_mov_b32_e32 v73, v125
	v_mov_b32_e32 v72, v125
	v_mov_b32_e32 v71, v125
	v_mov_b32_e32 v70, v125
	v_mov_b32_e32 v69, v125
	v_mov_b32_e32 v68, v125
	v_mov_b32_e32 v67, v125
	v_mov_b32_e32 v66, v125
	v_mov_b32_e32 v65, v125
	v_mov_b32_e32 v64, v125
	v_mov_b32_e32 v63, v125
	v_mov_b32_e32 v62, v125
	v_mov_b32_e32 v61, v125
	v_mov_b32_e32 v60, v125
	v_mov_b32_e32 v59, v125
	v_mov_b32_e32 v58, v125
	v_mov_b32_e32 v49, v125
	v_mov_b32_e32 v48, v125
	v_mov_b32_e32 v47, v125
	v_mov_b32_e32 v46, v125
	v_mov_b32_e32 v45, v125
	v_mov_b32_e32 v44, v125
	v_mov_b32_e32 v43, v125
	v_mov_b32_e32 v42, v125
	v_mov_b32_e32 v33, v125
	v_mov_b32_e32 v32, v125
	v_mov_b32_e32 v31, v125
	v_mov_b32_e32 v30, v125
	v_mov_b32_e32 v29, v125
	v_mov_b32_e32 v28, v125
	v_mov_b32_e32 v27, v125
	v_mov_b32_e32 v26, v125
	v_mov_b32_e32 v17, v125
	v_mov_b32_e32 v16, v125
	v_mov_b32_e32 v15, v125
	v_mov_b32_e32 v14, v125
	v_mov_b32_e32 v13, v125
	v_mov_b32_e32 v12, v125
	v_mov_b32_e32 v11, v125
	v_mov_b32_e32 v10, v125
	v_mov_b32_e32 v57, v125
	v_mov_b32_e32 v56, v125
	v_mov_b32_e32 v55, v125
	v_mov_b32_e32 v54, v125
	v_mov_b32_e32 v53, v125
	v_mov_b32_e32 v52, v125
	v_mov_b32_e32 v51, v125
	v_mov_b32_e32 v50, v125
	v_mov_b32_e32 v41, v125
	v_mov_b32_e32 v40, v125
	v_mov_b32_e32 v39, v125
	v_mov_b32_e32 v38, v125
	v_mov_b32_e32 v37, v125
	v_mov_b32_e32 v36, v125
	v_mov_b32_e32 v35, v125
	v_mov_b32_e32 v34, v125
	v_mov_b32_e32 v25, v125
	v_mov_b32_e32 v24, v125
	v_mov_b32_e32 v23, v125
	v_mov_b32_e32 v22, v125
	v_mov_b32_e32 v21, v125
	v_mov_b32_e32 v20, v125
	v_mov_b32_e32 v19, v125
	v_mov_b32_e32 v18, v125
	v_mov_b32_e32 v9, v125
	v_mov_b32_e32 v8, v125
	v_mov_b32_e32 v7, v125
	v_mov_b32_e32 v6, v125
	v_mov_b32_e32 v5, v125
	v_mov_b32_e32 v4, v125
	v_mov_b32_e32 v3, v125
	v_mov_b32_e32 v2, v125
	s_cbranch_vccnz .LBB0_537
	s_add_u32 s6, s54, 0x80
	s_addc_u32 s7, s55, 0
	s_add_u32 s54, s52, 0x100
	v_mov_b32_e32 v2, 0
	s_addc_u32 s55, s53, 0
	s_mov_b32 s52, 0
	v_mov_b32_e32 v3, v2
	v_mov_b32_e32 v4, v2
	v_mov_b32_e32 v5, v2
	v_mov_b32_e32 v6, v2
	v_mov_b32_e32 v7, v2
	v_mov_b32_e32 v8, v2
	v_mov_b32_e32 v9, v2
	v_mov_b32_e32 v18, v2
	v_mov_b32_e32 v19, v2
	v_mov_b32_e32 v20, v2
	v_mov_b32_e32 v21, v2
	v_mov_b32_e32 v22, v2
	v_mov_b32_e32 v23, v2
	v_mov_b32_e32 v24, v2
	v_mov_b32_e32 v25, v2
	v_mov_b32_e32 v34, v2
	v_mov_b32_e32 v35, v2
	v_mov_b32_e32 v36, v2
	v_mov_b32_e32 v37, v2
	v_mov_b32_e32 v38, v2
	v_mov_b32_e32 v39, v2
	v_mov_b32_e32 v40, v2
	v_mov_b32_e32 v41, v2
	v_mov_b32_e32 v50, v2
	v_mov_b32_e32 v51, v2
	v_mov_b32_e32 v52, v2
	v_mov_b32_e32 v53, v2
	v_mov_b32_e32 v54, v2
	v_mov_b32_e32 v55, v2
	v_mov_b32_e32 v56, v2
	v_mov_b32_e32 v57, v2
	v_mov_b32_e32 v10, v2
	v_mov_b32_e32 v11, v2
	v_mov_b32_e32 v12, v2
	v_mov_b32_e32 v13, v2
	v_mov_b32_e32 v14, v2
	v_mov_b32_e32 v15, v2
	v_mov_b32_e32 v16, v2
	v_mov_b32_e32 v17, v2
	v_mov_b32_e32 v26, v2
	v_mov_b32_e32 v27, v2
	v_mov_b32_e32 v28, v2
	v_mov_b32_e32 v29, v2
	v_mov_b32_e32 v30, v2
	v_mov_b32_e32 v31, v2
	v_mov_b32_e32 v32, v2
	v_mov_b32_e32 v33, v2
	v_mov_b32_e32 v42, v2
	v_mov_b32_e32 v43, v2
	v_mov_b32_e32 v44, v2
	v_mov_b32_e32 v45, v2
	v_mov_b32_e32 v46, v2
	v_mov_b32_e32 v47, v2
	v_mov_b32_e32 v48, v2
	v_mov_b32_e32 v49, v2
	v_mov_b32_e32 v58, v2
	v_mov_b32_e32 v59, v2
	v_mov_b32_e32 v60, v2
	v_mov_b32_e32 v61, v2
	v_mov_b32_e32 v62, v2
	v_mov_b32_e32 v63, v2
	v_mov_b32_e32 v64, v2
	v_mov_b32_e32 v65, v2
	v_mov_b32_e32 v66, v2
	v_mov_b32_e32 v67, v2
	v_mov_b32_e32 v68, v2
	v_mov_b32_e32 v69, v2
	v_mov_b32_e32 v70, v2
	v_mov_b32_e32 v71, v2
	v_mov_b32_e32 v72, v2
	v_mov_b32_e32 v73, v2
	v_mov_b32_e32 v82, v2
	v_mov_b32_e32 v83, v2
	v_mov_b32_e32 v84, v2
	v_mov_b32_e32 v85, v2
	v_mov_b32_e32 v86, v2
	v_mov_b32_e32 v87, v2
	v_mov_b32_e32 v88, v2
	v_mov_b32_e32 v89, v2
	v_mov_b32_e32 v98, v2
	v_mov_b32_e32 v99, v2
	v_mov_b32_e32 v100, v2
	v_mov_b32_e32 v101, v2
	v_mov_b32_e32 v102, v2
	v_mov_b32_e32 v103, v2
	v_mov_b32_e32 v104, v2
	v_mov_b32_e32 v105, v2
	v_mov_b32_e32 v114, v2
	v_mov_b32_e32 v115, v2
	v_mov_b32_e32 v116, v2
	v_mov_b32_e32 v117, v2
	v_mov_b32_e32 v118, v2
	v_mov_b32_e32 v119, v2
	v_mov_b32_e32 v120, v2
	v_mov_b32_e32 v121, v2
	v_mov_b32_e32 v74, v2
	v_mov_b32_e32 v75, v2
	v_mov_b32_e32 v76, v2
	v_mov_b32_e32 v77, v2
	v_mov_b32_e32 v78, v2
	v_mov_b32_e32 v79, v2
	v_mov_b32_e32 v80, v2
	v_mov_b32_e32 v81, v2
	v_mov_b32_e32 v90, v2
	v_mov_b32_e32 v91, v2
	v_mov_b32_e32 v92, v2
	v_mov_b32_e32 v93, v2
	v_mov_b32_e32 v94, v2
	v_mov_b32_e32 v95, v2
	v_mov_b32_e32 v96, v2
	v_mov_b32_e32 v97, v2
	v_mov_b32_e32 v106, v2
	v_mov_b32_e32 v107, v2
	v_mov_b32_e32 v108, v2
	v_mov_b32_e32 v109, v2
	v_mov_b32_e32 v110, v2
	v_mov_b32_e32 v111, v2
	v_mov_b32_e32 v112, v2
	v_mov_b32_e32 v113, v2
	v_mov_b32_e32 v126, v2
	v_mov_b32_e32 v127, v2
	v_mov_b32_e32 v128, v2
	v_mov_b32_e32 v129, v2
	v_mov_b32_e32 v122, v2
	v_mov_b32_e32 v123, v2
	v_mov_b32_e32 v124, v2
	v_mov_b32_e32 v125, v2
	.p2align	6

; template <class Epi, class Sched>
; __device__ __forceinline__ void gemm_phase(PG8_LAS unsigned char* lds, const Gemm g, const Sched& S, const Epi& E) {
;     ...
;         for (int t = 0; t < nt; t += 2) {
;             const bool last = (t == nt - 2);
;             const char* a1 = cA + (size_t)(t + 1) * kstep;
;             const char* a2 = last ? nA : cA + (size_t)(t + 2) * kstep; const char* b2 = last ? nB : cB + (size_t)(t + 2) * kstep;
;             const char* a3 = a2 + kstep; const char* b3 = b2 + kstep;
;     ...
; #pragma unroll
;         for (int a = 0; a < 2; ++a)
; #pragma unroll
;             for (int b = 0; b < 2; ++b)
; #pragma unroll
;                 for (int m = 0; m < 4; ++m)
; #pragma unroll
;                     for (int n = 0; n < 2; ++n) acc[a][b][m][n] = (f32x4){0.f, 0.f, 0.f, 0.f};
;         cur = nxt; cA = nA; cB = nB; ++ui;
.LBB0_623:
	v_mov_b32_e32 v129, 0
	s_andn2_b64 vcc, exec, s[30:31]
	v_mov_b32_e32 v128, v129
	v_mov_b32_e32 v127, v129
	v_mov_b32_e32 v126, v129
	v_mov_b32_e32 v125, v129
	v_mov_b32_e32 v124, v129
	v_mov_b32_e32 v123, v129
	v_mov_b32_e32 v122, v129
	v_mov_b32_e32 v113, v129
	v_mov_b32_e32 v112, v129
	v_mov_b32_e32 v111, v129
	v_mov_b32_e32 v110, v129
	v_mov_b32_e32 v109, v129
	v_mov_b32_e32 v108, v129
	v_mov_b32_e32 v107, v129
	v_mov_b32_e32 v106, v129
	v_mov_b32_e32 v97, v129
	v_mov_b32_e32 v96, v129
	v_mov_b32_e32 v95, v129
	v_mov_b32_e32 v94, v129
	v_mov_b32_e32 v93, v129
	v_mov_b32_e32 v92, v129
	v_mov_b32_e32 v91, v129
	v_mov_b32_e32 v90, v129
	v_mov_b32_e32 v81, v129
	v_mov_b32_e32 v80, v129
	v_mov_b32_e32 v79, v129
	v_mov_b32_e32 v78, v129
	v_mov_b32_e32 v77, v129
	v_mov_b32_e32 v76, v129
	v_mov_b32_e32 v75, v129
	v_mov_b32_e32 v74, v129
	v_mov_b32_e32 v121, v129
	v_mov_b32_e32 v120, v129
	v_mov_b32_e32 v119, v129
	v_mov_b32_e32 v118, v129
	v_mov_b32_e32 v117, v129
	v_mov_b32_e32 v116, v129
	v_mov_b32_e32 v115, v129
	v_mov_b32_e32 v114, v129
	v_mov_b32_e32 v105, v129
	v_mov_b32_e32 v104, v129
	v_mov_b32_e32 v103, v129
	v_mov_b32_e32 v102, v129
	v_mov_b32_e32 v101, v129
	v_mov_b32_e32 v100, v129
	v_mov_b32_e32 v99, v129
	v_mov_b32_e32 v98, v129
	v_mov_b32_e32 v89, v129
	v_mov_b32_e32 v88, v129
	v_mov_b32_e32 v87, v129
	v_mov_b32_e32 v86, v129
	v_mov_b32_e32 v85, v129
	v_mov_b32_e32 v84, v129
	v_mov_b32_e32 v83, v129
	v_mov_b32_e32 v82, v129
	v_mov_b32_e32 v73, v129
	v_mov_b32_e32 v72, v129
	v_mov_b32_e32 v71, v129
	v_mov_b32_e32 v70, v129
	v_mov_b32_e32 v69, v129
	v_mov_b32_e32 v68, v129
	v_mov_b32_e32 v67, v129
	v_mov_b32_e32 v66, v129
	v_mov_b32_e32 v65, v129
	v_mov_b32_e32 v64, v129
	v_mov_b32_e32 v63, v129
	v_mov_b32_e32 v62, v129
	v_mov_b32_e32 v61, v129
	v_mov_b32_e32 v60, v129
	v_mov_b32_e32 v59, v129
	v_mov_b32_e32 v58, v129
	v_mov_b32_e32 v49, v129
	v_mov_b32_e32 v48, v129
	v_mov_b32_e32 v47, v129
	v_mov_b32_e32 v46, v129
	v_mov_b32_e32 v45, v129
	v_mov_b32_e32 v44, v129
	v_mov_b32_e32 v43, v129
	v_mov_b32_e32 v42, v129
	v_mov_b32_e32 v33, v129
	v_mov_b32_e32 v32, v129
	v_mov_b32_e32 v31, v129
	v_mov_b32_e32 v30, v129
	v_mov_b32_e32 v29, v129
	v_mov_b32_e32 v28, v129
	v_mov_b32_e32 v27, v129
	v_mov_b32_e32 v26, v129
	v_mov_b32_e32 v17, v129
	v_mov_b32_e32 v16, v129
	v_mov_b32_e32 v15, v129
	v_mov_b32_e32 v14, v129
	v_mov_b32_e32 v13, v129
	v_mov_b32_e32 v12, v129
	v_mov_b32_e32 v11, v129
	v_mov_b32_e32 v10, v129
	v_mov_b32_e32 v57, v129
	v_mov_b32_e32 v56, v129
	v_mov_b32_e32 v55, v129
	v_mov_b32_e32 v54, v129
	v_mov_b32_e32 v53, v129
	v_mov_b32_e32 v52, v129
	v_mov_b32_e32 v51, v129
	v_mov_b32_e32 v50, v129
	v_mov_b32_e32 v41, v129
	v_mov_b32_e32 v40, v129
	v_mov_b32_e32 v39, v129
	v_mov_b32_e32 v38, v129
	v_mov_b32_e32 v37, v129
	v_mov_b32_e32 v36, v129
	v_mov_b32_e32 v35, v129
	v_mov_b32_e32 v34, v129
	v_mov_b32_e32 v25, v129
	v_mov_b32_e32 v24, v129
	v_mov_b32_e32 v23, v129
	v_mov_b32_e32 v22, v129
	v_mov_b32_e32 v21, v129
	v_mov_b32_e32 v20, v129
	v_mov_b32_e32 v19, v129
	v_mov_b32_e32 v18, v129
	v_mov_b32_e32 v9, v129
	v_mov_b32_e32 v8, v129
	v_mov_b32_e32 v7, v129
	v_mov_b32_e32 v6, v129
	v_mov_b32_e32 v5, v129
	v_mov_b32_e32 v4, v129
	v_mov_b32_e32 v3, v129
	v_mov_b32_e32 v2, v129
	s_cbranch_vccnz .LBB0_626
	s_add_u32 s44, s44, 0x80
	s_addc_u32 s45, s45, 0
	s_add_u32 s72, s50, 0x100
	v_mov_b32_e32 v2, 0
	s_addc_u32 s73, s51, 0
	s_mov_b32 s50, 0
	v_mov_b32_e32 v3, v2
	v_mov_b32_e32 v4, v2
	v_mov_b32_e32 v5, v2
	v_mov_b32_e32 v6, v2
	v_mov_b32_e32 v7, v2
	v_mov_b32_e32 v8, v2
	v_mov_b32_e32 v9, v2
	v_mov_b32_e32 v18, v2
	v_mov_b32_e32 v19, v2
	v_mov_b32_e32 v20, v2
	v_mov_b32_e32 v21, v2
	v_mov_b32_e32 v22, v2
	v_mov_b32_e32 v23, v2
	v_mov_b32_e32 v24, v2
	v_mov_b32_e32 v25, v2
	v_mov_b32_e32 v34, v2
	v_mov_b32_e32 v35, v2
	v_mov_b32_e32 v36, v2
	v_mov_b32_e32 v37, v2
	v_mov_b32_e32 v38, v2
	v_mov_b32_e32 v39, v2
	v_mov_b32_e32 v40, v2
	v_mov_b32_e32 v41, v2
	v_mov_b32_e32 v50, v2
	v_mov_b32_e32 v51, v2
	v_mov_b32_e32 v52, v2
	v_mov_b32_e32 v53, v2
	v_mov_b32_e32 v54, v2
	v_mov_b32_e32 v55, v2
	v_mov_b32_e32 v56, v2
	v_mov_b32_e32 v57, v2
	v_mov_b32_e32 v10, v2
	v_mov_b32_e32 v11, v2
	v_mov_b32_e32 v12, v2
	v_mov_b32_e32 v13, v2
	v_mov_b32_e32 v14, v2
	v_mov_b32_e32 v15, v2
	v_mov_b32_e32 v16, v2
	v_mov_b32_e32 v17, v2
	v_mov_b32_e32 v26, v2
	v_mov_b32_e32 v27, v2
	v_mov_b32_e32 v28, v2
	v_mov_b32_e32 v29, v2
	v_mov_b32_e32 v30, v2
	v_mov_b32_e32 v31, v2
	v_mov_b32_e32 v32, v2
	v_mov_b32_e32 v33, v2
	v_mov_b32_e32 v42, v2
	v_mov_b32_e32 v43, v2
	v_mov_b32_e32 v44, v2
	v_mov_b32_e32 v45, v2
	v_mov_b32_e32 v46, v2
	v_mov_b32_e32 v47, v2
	v_mov_b32_e32 v48, v2
	v_mov_b32_e32 v49, v2
	v_mov_b32_e32 v58, v2
	v_mov_b32_e32 v59, v2
	v_mov_b32_e32 v60, v2
	v_mov_b32_e32 v61, v2
	v_mov_b32_e32 v62, v2
	v_mov_b32_e32 v63, v2
	v_mov_b32_e32 v64, v2
	v_mov_b32_e32 v65, v2
	v_mov_b32_e32 v66, v2
	v_mov_b32_e32 v67, v2
	v_mov_b32_e32 v68, v2
	v_mov_b32_e32 v69, v2
	v_mov_b32_e32 v70, v2
	v_mov_b32_e32 v71, v2
	v_mov_b32_e32 v72, v2
	v_mov_b32_e32 v73, v2
	v_mov_b32_e32 v82, v2
	v_mov_b32_e32 v83, v2
	v_mov_b32_e32 v84, v2
	v_mov_b32_e32 v85, v2
	v_mov_b32_e32 v86, v2
	v_mov_b32_e32 v87, v2
	v_mov_b32_e32 v88, v2
	v_mov_b32_e32 v89, v2
	v_mov_b32_e32 v98, v2
	v_mov_b32_e32 v99, v2
	v_mov_b32_e32 v100, v2
	v_mov_b32_e32 v101, v2
	v_mov_b32_e32 v102, v2
	v_mov_b32_e32 v103, v2
	v_mov_b32_e32 v104, v2
	v_mov_b32_e32 v105, v2
	v_mov_b32_e32 v114, v2
	v_mov_b32_e32 v115, v2
	v_mov_b32_e32 v116, v2
	v_mov_b32_e32 v117, v2
	v_mov_b32_e32 v118, v2
	v_mov_b32_e32 v119, v2
	v_mov_b32_e32 v120, v2
	v_mov_b32_e32 v121, v2
	v_mov_b32_e32 v74, v2
	v_mov_b32_e32 v75, v2
	v_mov_b32_e32 v76, v2
	v_mov_b32_e32 v77, v2
	v_mov_b32_e32 v78, v2
	v_mov_b32_e32 v79, v2
	v_mov_b32_e32 v80, v2
	v_mov_b32_e32 v81, v2
	v_mov_b32_e32 v90, v2
	v_mov_b32_e32 v91, v2
	v_mov_b32_e32 v92, v2
	v_mov_b32_e32 v93, v2
	v_mov_b32_e32 v94, v2
	v_mov_b32_e32 v95, v2
	v_mov_b32_e32 v96, v2
	v_mov_b32_e32 v97, v2
	v_mov_b32_e32 v106, v2
	v_mov_b32_e32 v107, v2
	v_mov_b32_e32 v108, v2
	v_mov_b32_e32 v109, v2
	v_mov_b32_e32 v110, v2
	v_mov_b32_e32 v111, v2
	v_mov_b32_e32 v112, v2
	v_mov_b32_e32 v113, v2
	v_mov_b32_e32 v122, v2
	v_mov_b32_e32 v123, v2
	v_mov_b32_e32 v124, v2
	v_mov_b32_e32 v125, v2
	v_mov_b32_e32 v126, v2
	v_mov_b32_e32 v127, v2
	v_mov_b32_e32 v128, v2
	v_mov_b32_e32 v129, v2
	.p2align	6

; template <class Epi, class Sched>
; __device__ __forceinline__ void gemm_phase(PG8_LAS unsigned char* lds, const Gemm g, const Sched& S, const Epi& E) {
;     ...
;         for (int t = 0; t < nt; t += 2) {
;             const bool last = (t == nt - 2);
;             const char* a1 = cA + (size_t)(t + 1) * kstep;
;             const char* a2 = last ? nA : cA + (size_t)(t + 2) * kstep; const char* b2 = last ? nB : cB + (size_t)(t + 2) * kstep;
;             const char* a3 = a2 + kstep; const char* b3 = b2 + kstep;
;     ...
; #pragma unroll
;         for (int a = 0; a < 2; ++a)
; #pragma unroll
;             for (int b = 0; b < 2; ++b)
; #pragma unroll
;                 for (int m = 0; m < 4; ++m)
; #pragma unroll
;                     for (int n = 0; n < 2; ++n) acc[a][b][m][n] = (f32x4){0.f, 0.f, 0.f, 0.f};
;         cur = nxt; cA = nA; cB = nB; ++ui;
.LBB0_647:
	v_mov_b32_e32 v125, 0
	s_andn2_b64 vcc, exec, s[30:31]
	v_mov_b32_e32 v124, v125
	v_mov_b32_e32 v123, v125
	v_mov_b32_e32 v122, v125
	v_mov_b32_e32 v129, v125
	v_mov_b32_e32 v128, v125
	v_mov_b32_e32 v127, v125
	v_mov_b32_e32 v126, v125
	v_mov_b32_e32 v113, v125
	v_mov_b32_e32 v112, v125
	v_mov_b32_e32 v111, v125
	v_mov_b32_e32 v110, v125
	v_mov_b32_e32 v109, v125
	v_mov_b32_e32 v108, v125
	v_mov_b32_e32 v107, v125
	v_mov_b32_e32 v106, v125
	v_mov_b32_e32 v97, v125
	v_mov_b32_e32 v96, v125
	v_mov_b32_e32 v95, v125
	v_mov_b32_e32 v94, v125
	v_mov_b32_e32 v93, v125
	v_mov_b32_e32 v92, v125
	v_mov_b32_e32 v91, v125
	v_mov_b32_e32 v90, v125
	v_mov_b32_e32 v81, v125
	v_mov_b32_e32 v80, v125
	v_mov_b32_e32 v79, v125
	v_mov_b32_e32 v78, v125
	v_mov_b32_e32 v77, v125
	v_mov_b32_e32 v76, v125
	v_mov_b32_e32 v75, v125
	v_mov_b32_e32 v74, v125
	v_mov_b32_e32 v121, v125
	v_mov_b32_e32 v120, v125
	v_mov_b32_e32 v119, v125
	v_mov_b32_e32 v118, v125
	v_mov_b32_e32 v117, v125
	v_mov_b32_e32 v116, v125
	v_mov_b32_e32 v115, v125
	v_mov_b32_e32 v114, v125
	v_mov_b32_e32 v105, v125
	v_mov_b32_e32 v104, v125
	v_mov_b32_e32 v103, v125
	v_mov_b32_e32 v102, v125
	v_mov_b32_e32 v101, v125
	v_mov_b32_e32 v100, v125
	v_mov_b32_e32 v99, v125
	v_mov_b32_e32 v98, v125
	v_mov_b32_e32 v89, v125
	v_mov_b32_e32 v88, v125
	v_mov_b32_e32 v87, v125
	v_mov_b32_e32 v86, v125
	v_mov_b32_e32 v85, v125
	v_mov_b32_e32 v84, v125
	v_mov_b32_e32 v83, v125
	v_mov_b32_e32 v82, v125
	v_mov_b32_e32 v73, v125
	v_mov_b32_e32 v72, v125
	v_mov_b32_e32 v71, v125
	v_mov_b32_e32 v70, v125
	v_mov_b32_e32 v69, v125
	v_mov_b32_e32 v68, v125
	v_mov_b32_e32 v67, v125
	v_mov_b32_e32 v66, v125
	v_mov_b32_e32 v65, v125
	v_mov_b32_e32 v64, v125
	v_mov_b32_e32 v63, v125
	v_mov_b32_e32 v62, v125
	v_mov_b32_e32 v61, v125
	v_mov_b32_e32 v60, v125
	v_mov_b32_e32 v59, v125
	v_mov_b32_e32 v58, v125
	v_mov_b32_e32 v49, v125
	v_mov_b32_e32 v48, v125
	v_mov_b32_e32 v47, v125
	v_mov_b32_e32 v46, v125
	v_mov_b32_e32 v45, v125
	v_mov_b32_e32 v44, v125
	v_mov_b32_e32 v43, v125
	v_mov_b32_e32 v42, v125
	v_mov_b32_e32 v33, v125
	v_mov_b32_e32 v32, v125
	v_mov_b32_e32 v31, v125
	v_mov_b32_e32 v30, v125
	v_mov_b32_e32 v29, v125
	v_mov_b32_e32 v28, v125
	v_mov_b32_e32 v27, v125
	v_mov_b32_e32 v26, v125
	v_mov_b32_e32 v17, v125
	v_mov_b32_e32 v16, v125
	v_mov_b32_e32 v15, v125
	v_mov_b32_e32 v14, v125
	v_mov_b32_e32 v13, v125
	v_mov_b32_e32 v12, v125
	v_mov_b32_e32 v11, v125
	v_mov_b32_e32 v10, v125
	v_mov_b32_e32 v57, v125
	v_mov_b32_e32 v56, v125
	v_mov_b32_e32 v55, v125
	v_mov_b32_e32 v54, v125
	v_mov_b32_e32 v53, v125
	v_mov_b32_e32 v52, v125
	v_mov_b32_e32 v51, v125
	v_mov_b32_e32 v50, v125
	v_mov_b32_e32 v41, v125
	v_mov_b32_e32 v40, v125
	v_mov_b32_e32 v39, v125
	v_mov_b32_e32 v38, v125
	v_mov_b32_e32 v37, v125
	v_mov_b32_e32 v36, v125
	v_mov_b32_e32 v35, v125
	v_mov_b32_e32 v34, v125
	v_mov_b32_e32 v25, v125
	v_mov_b32_e32 v24, v125
	v_mov_b32_e32 v23, v125
	v_mov_b32_e32 v22, v125
	v_mov_b32_e32 v21, v125
	v_mov_b32_e32 v20, v125
	v_mov_b32_e32 v19, v125
	v_mov_b32_e32 v18, v125
	v_mov_b32_e32 v9, v125
	v_mov_b32_e32 v8, v125
	v_mov_b32_e32 v7, v125
	v_mov_b32_e32 v6, v125
	v_mov_b32_e32 v5, v125
	v_mov_b32_e32 v4, v125
	v_mov_b32_e32 v3, v125
	v_mov_b32_e32 v2, v125
	s_cbranch_vccnz .LBB0_650
	s_add_u32 s42, s42, 0x80
	s_addc_u32 s43, s43, 0
	s_add_u32 s73, s44, 0x100
	v_mov_b32_e32 v2, 0
	s_addc_u32 s74, s45, 0
	s_mov_b32 s44, 0
	v_mov_b32_e32 v3, v2
	v_mov_b32_e32 v4, v2
	v_mov_b32_e32 v5, v2
	v_mov_b32_e32 v6, v2
	v_mov_b32_e32 v7, v2
	v_mov_b32_e32 v8, v2
	v_mov_b32_e32 v9, v2
	v_mov_b32_e32 v18, v2
	v_mov_b32_e32 v19, v2
	v_mov_b32_e32 v20, v2
	v_mov_b32_e32 v21, v2
	v_mov_b32_e32 v22, v2
	v_mov_b32_e32 v23, v2
	v_mov_b32_e32 v24, v2
	v_mov_b32_e32 v25, v2
	v_mov_b32_e32 v34, v2
	v_mov_b32_e32 v35, v2
	v_mov_b32_e32 v36, v2
	v_mov_b32_e32 v37, v2
	v_mov_b32_e32 v38, v2
	v_mov_b32_e32 v39, v2
	v_mov_b32_e32 v40, v2
	v_mov_b32_e32 v41, v2
	v_mov_b32_e32 v50, v2
	v_mov_b32_e32 v51, v2
	v_mov_b32_e32 v52, v2
	v_mov_b32_e32 v53, v2
	v_mov_b32_e32 v54, v2
	v_mov_b32_e32 v55, v2
	v_mov_b32_e32 v56, v2
	v_mov_b32_e32 v57, v2
	v_mov_b32_e32 v10, v2
	v_mov_b32_e32 v11, v2
	v_mov_b32_e32 v12, v2
	v_mov_b32_e32 v13, v2
	v_mov_b32_e32 v14, v2
	v_mov_b32_e32 v15, v2
	v_mov_b32_e32 v16, v2
	v_mov_b32_e32 v17, v2
	v_mov_b32_e32 v26, v2
	v_mov_b32_e32 v27, v2
	v_mov_b32_e32 v28, v2
	v_mov_b32_e32 v29, v2
	v_mov_b32_e32 v30, v2
	v_mov_b32_e32 v31, v2
	v_mov_b32_e32 v32, v2
	v_mov_b32_e32 v33, v2
	v_mov_b32_e32 v42, v2
	v_mov_b32_e32 v43, v2
	v_mov_b32_e32 v44, v2
	v_mov_b32_e32 v45, v2
	v_mov_b32_e32 v46, v2
	v_mov_b32_e32 v47, v2
	v_mov_b32_e32 v48, v2
	v_mov_b32_e32 v49, v2
	v_mov_b32_e32 v58, v2
	v_mov_b32_e32 v59, v2
	v_mov_b32_e32 v60, v2
	v_mov_b32_e32 v61, v2
	v_mov_b32_e32 v62, v2
	v_mov_b32_e32 v63, v2
	v_mov_b32_e32 v64, v2
	v_mov_b32_e32 v65, v2
	v_mov_b32_e32 v66, v2
	v_mov_b32_e32 v67, v2
	v_mov_b32_e32 v68, v2
	v_mov_b32_e32 v69, v2
	v_mov_b32_e32 v70, v2
	v_mov_b32_e32 v71, v2
	v_mov_b32_e32 v72, v2
	v_mov_b32_e32 v73, v2
	v_mov_b32_e32 v82, v2
	v_mov_b32_e32 v83, v2
	v_mov_b32_e32 v84, v2
	v_mov_b32_e32 v85, v2
	v_mov_b32_e32 v86, v2
	v_mov_b32_e32 v87, v2
	v_mov_b32_e32 v88, v2
	v_mov_b32_e32 v89, v2
	v_mov_b32_e32 v98, v2
	v_mov_b32_e32 v99, v2
	v_mov_b32_e32 v100, v2
	v_mov_b32_e32 v101, v2
	v_mov_b32_e32 v102, v2
	v_mov_b32_e32 v103, v2
	v_mov_b32_e32 v104, v2
	v_mov_b32_e32 v105, v2
	v_mov_b32_e32 v114, v2
	v_mov_b32_e32 v115, v2
	v_mov_b32_e32 v116, v2
	v_mov_b32_e32 v117, v2
	v_mov_b32_e32 v118, v2
	v_mov_b32_e32 v119, v2
	v_mov_b32_e32 v120, v2
	v_mov_b32_e32 v121, v2
	v_mov_b32_e32 v74, v2
	v_mov_b32_e32 v75, v2
	v_mov_b32_e32 v76, v2
	v_mov_b32_e32 v77, v2
	v_mov_b32_e32 v78, v2
	v_mov_b32_e32 v79, v2
	v_mov_b32_e32 v80, v2
	v_mov_b32_e32 v81, v2
	v_mov_b32_e32 v90, v2
	v_mov_b32_e32 v91, v2
	v_mov_b32_e32 v92, v2
	v_mov_b32_e32 v93, v2
	v_mov_b32_e32 v94, v2
	v_mov_b32_e32 v95, v2
	v_mov_b32_e32 v96, v2
	v_mov_b32_e32 v97, v2
	v_mov_b32_e32 v106, v2
	v_mov_b32_e32 v107, v2
	v_mov_b32_e32 v108, v2
	v_mov_b32_e32 v109, v2
	v_mov_b32_e32 v110, v2
	v_mov_b32_e32 v111, v2
	v_mov_b32_e32 v112, v2
	v_mov_b32_e32 v113, v2
	v_mov_b32_e32 v126, v2
	v_mov_b32_e32 v127, v2
	v_mov_b32_e32 v128, v2
	v_mov_b32_e32 v129, v2
	v_mov_b32_e32 v122, v2
	v_mov_b32_e32 v123, v2
	v_mov_b32_e32 v124, v2
	v_mov_b32_e32 v125, v2
	.p2align	6

; template <class Epi, class Sched>
; __device__ __forceinline__ void gemm_phase(PG8_LAS unsigned char* lds, const Gemm g, const Sched& S, const Epi& E) {
;     ...
;         for (int t = 0; t < nt; t += 2) {
;             const bool last = (t == nt - 2);
;             const char* a1 = cA + (size_t)(t + 1) * kstep;
;             const char* a2 = last ? nA : cA + (size_t)(t + 2) * kstep; const char* b2 = last ? nB : cB + (size_t)(t + 2) * kstep;
;             const char* a3 = a2 + kstep; const char* b3 = b2 + kstep;
;     ...
; #pragma unroll
;         for (int a = 0; a < 2; ++a)
; #pragma unroll
;             for (int b = 0; b < 2; ++b)
; #pragma unroll
;                 for (int m = 0; m < 4; ++m)
; #pragma unroll
;                     for (int n = 0; n < 2; ++n) acc[a][b][m][n] = (f32x4){0.f, 0.f, 0.f, 0.f};
;         cur = nxt; cA = nA; cB = nB; ++ui;
.LBB0_762:
	v_mov_b32_e32 v129, 0
	s_andn2_b64 vcc, exec, s[20:21]
	v_mov_b32_e32 v128, v129
	v_mov_b32_e32 v127, v129
	v_mov_b32_e32 v126, v129
	v_mov_b32_e32 v125, v129
	v_mov_b32_e32 v124, v129
	v_mov_b32_e32 v123, v129
	v_mov_b32_e32 v122, v129
	v_mov_b32_e32 v113, v129
	v_mov_b32_e32 v112, v129
	v_mov_b32_e32 v111, v129
	v_mov_b32_e32 v110, v129
	v_mov_b32_e32 v109, v129
	v_mov_b32_e32 v108, v129
	v_mov_b32_e32 v107, v129
	v_mov_b32_e32 v106, v129
	v_mov_b32_e32 v97, v129
	v_mov_b32_e32 v96, v129
	v_mov_b32_e32 v95, v129
	v_mov_b32_e32 v94, v129
	v_mov_b32_e32 v93, v129
	v_mov_b32_e32 v92, v129
	v_mov_b32_e32 v91, v129
	v_mov_b32_e32 v90, v129
	v_mov_b32_e32 v81, v129
	v_mov_b32_e32 v80, v129
	v_mov_b32_e32 v79, v129
	v_mov_b32_e32 v78, v129
	v_mov_b32_e32 v77, v129
	v_mov_b32_e32 v76, v129
	v_mov_b32_e32 v75, v129
	v_mov_b32_e32 v74, v129
	v_mov_b32_e32 v121, v129
	v_mov_b32_e32 v120, v129
	v_mov_b32_e32 v119, v129
	v_mov_b32_e32 v118, v129
	v_mov_b32_e32 v117, v129
	v_mov_b32_e32 v116, v129
	v_mov_b32_e32 v115, v129
	v_mov_b32_e32 v114, v129
	v_mov_b32_e32 v105, v129
	v_mov_b32_e32 v104, v129
	v_mov_b32_e32 v103, v129
	v_mov_b32_e32 v102, v129
	v_mov_b32_e32 v101, v129
	v_mov_b32_e32 v100, v129
	v_mov_b32_e32 v99, v129
	v_mov_b32_e32 v98, v129
	v_mov_b32_e32 v89, v129
	v_mov_b32_e32 v88, v129
	v_mov_b32_e32 v87, v129
	v_mov_b32_e32 v86, v129
	v_mov_b32_e32 v85, v129
	v_mov_b32_e32 v84, v129
	v_mov_b32_e32 v83, v129
	v_mov_b32_e32 v82, v129
	v_mov_b32_e32 v73, v129
	v_mov_b32_e32 v72, v129
	v_mov_b32_e32 v71, v129
	v_mov_b32_e32 v70, v129
	v_mov_b32_e32 v69, v129
	v_mov_b32_e32 v68, v129
	v_mov_b32_e32 v67, v129
	v_mov_b32_e32 v66, v129
	v_mov_b32_e32 v65, v129
	v_mov_b32_e32 v64, v129
	v_mov_b32_e32 v63, v129
	v_mov_b32_e32 v62, v129
	v_mov_b32_e32 v61, v129
	v_mov_b32_e32 v60, v129
	v_mov_b32_e32 v59, v129
	v_mov_b32_e32 v58, v129
	v_mov_b32_e32 v49, v129
	v_mov_b32_e32 v48, v129
	v_mov_b32_e32 v47, v129
	v_mov_b32_e32 v46, v129
	v_mov_b32_e32 v45, v129
	v_mov_b32_e32 v44, v129
	v_mov_b32_e32 v43, v129
	v_mov_b32_e32 v42, v129
	v_mov_b32_e32 v33, v129
	v_mov_b32_e32 v32, v129
	v_mov_b32_e32 v31, v129
	v_mov_b32_e32 v30, v129
	v_mov_b32_e32 v29, v129
	v_mov_b32_e32 v28, v129
	v_mov_b32_e32 v27, v129
	v_mov_b32_e32 v26, v129
	v_mov_b32_e32 v17, v129
	v_mov_b32_e32 v16, v129
	v_mov_b32_e32 v15, v129
	v_mov_b32_e32 v14, v129
	v_mov_b32_e32 v13, v129
	v_mov_b32_e32 v12, v129
	v_mov_b32_e32 v11, v129
	v_mov_b32_e32 v10, v129
	v_mov_b32_e32 v57, v129
	v_mov_b32_e32 v56, v129
	v_mov_b32_e32 v55, v129
	v_mov_b32_e32 v54, v129
	v_mov_b32_e32 v53, v129
	v_mov_b32_e32 v52, v129
	v_mov_b32_e32 v51, v129
	v_mov_b32_e32 v50, v129
	v_mov_b32_e32 v41, v129
	v_mov_b32_e32 v40, v129
	v_mov_b32_e32 v39, v129
	v_mov_b32_e32 v38, v129
	v_mov_b32_e32 v37, v129
	v_mov_b32_e32 v36, v129
	v_mov_b32_e32 v35, v129
	v_mov_b32_e32 v34, v129
	v_mov_b32_e32 v25, v129
	v_mov_b32_e32 v24, v129
	v_mov_b32_e32 v23, v129
	v_mov_b32_e32 v22, v129
	v_mov_b32_e32 v21, v129
	v_mov_b32_e32 v20, v129
	v_mov_b32_e32 v19, v129
	v_mov_b32_e32 v18, v129
	v_mov_b32_e32 v9, v129
	v_mov_b32_e32 v8, v129
	v_mov_b32_e32 v7, v129
	v_mov_b32_e32 v6, v129
	v_mov_b32_e32 v5, v129
	v_mov_b32_e32 v4, v129
	v_mov_b32_e32 v3, v129
	v_mov_b32_e32 v2, v129
	s_cbranch_vccnz .LBB0_765
	s_add_u32 s30, s30, 0x80
	v_mov_b32_e32 v2, 0
	s_addc_u32 s31, s31, 0
	s_mov_b32 s40, 0
	s_mov_b64 s[38:39], 0x100
	v_mov_b32_e32 v3, v2
	v_mov_b32_e32 v4, v2
	v_mov_b32_e32 v5, v2
	v_mov_b32_e32 v6, v2
	v_mov_b32_e32 v7, v2
	v_mov_b32_e32 v8, v2
	v_mov_b32_e32 v9, v2
	v_mov_b32_e32 v18, v2
	v_mov_b32_e32 v19, v2
	v_mov_b32_e32 v20, v2
	v_mov_b32_e32 v21, v2
	v_mov_b32_e32 v22, v2
	v_mov_b32_e32 v23, v2
	v_mov_b32_e32 v24, v2
	v_mov_b32_e32 v25, v2
	v_mov_b32_e32 v34, v2
	v_mov_b32_e32 v35, v2
	v_mov_b32_e32 v36, v2
	v_mov_b32_e32 v37, v2
	v_mov_b32_e32 v38, v2
	v_mov_b32_e32 v39, v2
	v_mov_b32_e32 v40, v2
	v_mov_b32_e32 v41, v2
	v_mov_b32_e32 v50, v2
	v_mov_b32_e32 v51, v2
	v_mov_b32_e32 v52, v2
	v_mov_b32_e32 v53, v2
	v_mov_b32_e32 v54, v2
	v_mov_b32_e32 v55, v2
	v_mov_b32_e32 v56, v2
	v_mov_b32_e32 v57, v2
	v_mov_b32_e32 v10, v2
	v_mov_b32_e32 v11, v2
	v_mov_b32_e32 v12, v2
	v_mov_b32_e32 v13, v2
	v_mov_b32_e32 v14, v2
	v_mov_b32_e32 v15, v2
	v_mov_b32_e32 v16, v2
	v_mov_b32_e32 v17, v2
	v_mov_b32_e32 v26, v2
	v_mov_b32_e32 v27, v2
	v_mov_b32_e32 v28, v2
	v_mov_b32_e32 v29, v2
	v_mov_b32_e32 v30, v2
	v_mov_b32_e32 v31, v2
	v_mov_b32_e32 v32, v2
	v_mov_b32_e32 v33, v2
	v_mov_b32_e32 v42, v2
	v_mov_b32_e32 v43, v2
	v_mov_b32_e32 v44, v2
	v_mov_b32_e32 v45, v2
	v_mov_b32_e32 v46, v2
	v_mov_b32_e32 v47, v2
	v_mov_b32_e32 v48, v2
	v_mov_b32_e32 v49, v2
	v_mov_b32_e32 v58, v2
	v_mov_b32_e32 v59, v2
	v_mov_b32_e32 v60, v2
	v_mov_b32_e32 v61, v2
	v_mov_b32_e32 v62, v2
	v_mov_b32_e32 v63, v2
	v_mov_b32_e32 v64, v2
	v_mov_b32_e32 v65, v2
	v_mov_b32_e32 v66, v2
	v_mov_b32_e32 v67, v2
	v_mov_b32_e32 v68, v2
	v_mov_b32_e32 v69, v2
	v_mov_b32_e32 v70, v2
	v_mov_b32_e32 v71, v2
	v_mov_b32_e32 v72, v2
	v_mov_b32_e32 v73, v2
	v_mov_b32_e32 v82, v2
	v_mov_b32_e32 v83, v2
	v_mov_b32_e32 v84, v2
	v_mov_b32_e32 v85, v2
	v_mov_b32_e32 v86, v2
	v_mov_b32_e32 v87, v2
	v_mov_b32_e32 v88, v2
	v_mov_b32_e32 v89, v2
	v_mov_b32_e32 v98, v2
	v_mov_b32_e32 v99, v2
	v_mov_b32_e32 v100, v2
	v_mov_b32_e32 v101, v2
	v_mov_b32_e32 v102, v2
	v_mov_b32_e32 v103, v2
	v_mov_b32_e32 v104, v2
	v_mov_b32_e32 v105, v2
	v_mov_b32_e32 v114, v2
	v_mov_b32_e32 v115, v2
	v_mov_b32_e32 v116, v2
	v_mov_b32_e32 v117, v2
	v_mov_b32_e32 v118, v2
	v_mov_b32_e32 v119, v2
	v_mov_b32_e32 v120, v2
	v_mov_b32_e32 v121, v2
	v_mov_b32_e32 v74, v2
	v_mov_b32_e32 v75, v2
	v_mov_b32_e32 v76, v2
	v_mov_b32_e32 v77, v2
	v_mov_b32_e32 v78, v2
	v_mov_b32_e32 v79, v2
	v_mov_b32_e32 v80, v2
	v_mov_b32_e32 v81, v2
	v_mov_b32_e32 v90, v2
	v_mov_b32_e32 v91, v2
	v_mov_b32_e32 v92, v2
	v_mov_b32_e32 v93, v2
	v_mov_b32_e32 v94, v2
	v_mov_b32_e32 v95, v2
	v_mov_b32_e32 v96, v2
	v_mov_b32_e32 v97, v2
	v_mov_b32_e32 v106, v2
	v_mov_b32_e32 v107, v2
	v_mov_b32_e32 v108, v2
	v_mov_b32_e32 v109, v2
	v_mov_b32_e32 v110, v2
	v_mov_b32_e32 v111, v2
	v_mov_b32_e32 v112, v2
	v_mov_b32_e32 v113, v2
	v_mov_b32_e32 v122, v2
	v_mov_b32_e32 v123, v2
	v_mov_b32_e32 v124, v2
	v_mov_b32_e32 v125, v2
	v_mov_b32_e32 v126, v2
	v_mov_b32_e32 v127, v2
	v_mov_b32_e32 v128, v2
	v_mov_b32_e32 v129, v2
	.p2align	6

; template <class Epi, class Sched>
; __device__ __forceinline__ void gemm_phase(PG8_LAS unsigned char* lds, const Gemm g, const Sched& S, const Epi& E) {
;     ...
;         for (int t = 0; t < nt; t += 2) {
;             const bool last = (t == nt - 2);
;             const char* a1 = cA + (size_t)(t + 1) * kstep;
;             const char* a2 = last ? nA : cA + (size_t)(t + 2) * kstep; const char* b2 = last ? nB : cB + (size_t)(t + 2) * kstep;
;             const char* a3 = a2 + kstep; const char* b3 = b2 + kstep;
;     ...
; #pragma unroll
;         for (int a = 0; a < 2; ++a)
; #pragma unroll
;             for (int b = 0; b < 2; ++b)
; #pragma unroll
;                 for (int m = 0; m < 4; ++m)
; #pragma unroll
;                     for (int n = 0; n < 2; ++n) acc[a][b][m][n] = (f32x4){0.f, 0.f, 0.f, 0.f};
;         cur = nxt; cA = nA; cB = nB; ++ui;
.LBB0_1200:
	v_mov_b32_e32 v125, 0
	s_andn2_b64 vcc, exec, s[42:43]
	v_mov_b32_e32 v124, v125
	v_mov_b32_e32 v123, v125
	v_mov_b32_e32 v122, v125
	v_mov_b32_e32 v129, v125
	v_mov_b32_e32 v128, v125
	v_mov_b32_e32 v127, v125
	v_mov_b32_e32 v126, v125
	v_mov_b32_e32 v113, v125
	v_mov_b32_e32 v112, v125
	v_mov_b32_e32 v111, v125
	v_mov_b32_e32 v110, v125
	v_mov_b32_e32 v109, v125
	v_mov_b32_e32 v108, v125
	v_mov_b32_e32 v107, v125
	v_mov_b32_e32 v106, v125
	v_mov_b32_e32 v97, v125
	v_mov_b32_e32 v96, v125
	v_mov_b32_e32 v95, v125
	v_mov_b32_e32 v94, v125
	v_mov_b32_e32 v93, v125
	v_mov_b32_e32 v92, v125
	v_mov_b32_e32 v91, v125
	v_mov_b32_e32 v90, v125
	v_mov_b32_e32 v81, v125
	v_mov_b32_e32 v80, v125
	v_mov_b32_e32 v79, v125
	v_mov_b32_e32 v78, v125
	v_mov_b32_e32 v77, v125
	v_mov_b32_e32 v76, v125
	v_mov_b32_e32 v75, v125
	v_mov_b32_e32 v74, v125
	v_mov_b32_e32 v121, v125
	v_mov_b32_e32 v120, v125
	v_mov_b32_e32 v119, v125
	v_mov_b32_e32 v118, v125
	v_mov_b32_e32 v117, v125
	v_mov_b32_e32 v116, v125
	v_mov_b32_e32 v115, v125
	v_mov_b32_e32 v114, v125
	v_mov_b32_e32 v105, v125
	v_mov_b32_e32 v104, v125
	v_mov_b32_e32 v103, v125
	v_mov_b32_e32 v102, v125
	v_mov_b32_e32 v101, v125
	v_mov_b32_e32 v100, v125
	v_mov_b32_e32 v99, v125
	v_mov_b32_e32 v98, v125
	v_mov_b32_e32 v89, v125
	v_mov_b32_e32 v88, v125
	v_mov_b32_e32 v87, v125
	v_mov_b32_e32 v86, v125
	v_mov_b32_e32 v85, v125
	v_mov_b32_e32 v84, v125
	v_mov_b32_e32 v83, v125
	v_mov_b32_e32 v82, v125
	v_mov_b32_e32 v73, v125
	v_mov_b32_e32 v72, v125
	v_mov_b32_e32 v71, v125
	v_mov_b32_e32 v70, v125
	v_mov_b32_e32 v69, v125
	v_mov_b32_e32 v68, v125
	v_mov_b32_e32 v67, v125
	v_mov_b32_e32 v66, v125
	v_mov_b32_e32 v65, v125
	v_mov_b32_e32 v64, v125
	v_mov_b32_e32 v63, v125
	v_mov_b32_e32 v62, v125
	v_mov_b32_e32 v61, v125
	v_mov_b32_e32 v60, v125
	v_mov_b32_e32 v59, v125
	v_mov_b32_e32 v58, v125
	v_mov_b32_e32 v49, v125
	v_mov_b32_e32 v48, v125
	v_mov_b32_e32 v47, v125
	v_mov_b32_e32 v46, v125
	v_mov_b32_e32 v45, v125
	v_mov_b32_e32 v44, v125
	v_mov_b32_e32 v43, v125
	v_mov_b32_e32 v42, v125
	v_mov_b32_e32 v33, v125
	v_mov_b32_e32 v32, v125
	v_mov_b32_e32 v31, v125
	v_mov_b32_e32 v30, v125
	v_mov_b32_e32 v29, v125
	v_mov_b32_e32 v28, v125
	v_mov_b32_e32 v27, v125
	v_mov_b32_e32 v26, v125
	v_mov_b32_e32 v17, v125
	v_mov_b32_e32 v16, v125
	v_mov_b32_e32 v15, v125
	v_mov_b32_e32 v14, v125
	v_mov_b32_e32 v13, v125
	v_mov_b32_e32 v12, v125
	v_mov_b32_e32 v11, v125
	v_mov_b32_e32 v10, v125
	v_mov_b32_e32 v57, v125
	v_mov_b32_e32 v56, v125
	v_mov_b32_e32 v55, v125
	v_mov_b32_e32 v54, v125
	v_mov_b32_e32 v53, v125
	v_mov_b32_e32 v52, v125
	v_mov_b32_e32 v51, v125
	v_mov_b32_e32 v50, v125
	v_mov_b32_e32 v41, v125
	v_mov_b32_e32 v40, v125
	v_mov_b32_e32 v39, v125
	v_mov_b32_e32 v38, v125
	v_mov_b32_e32 v37, v125
	v_mov_b32_e32 v36, v125
	v_mov_b32_e32 v35, v125
	v_mov_b32_e32 v34, v125
	v_mov_b32_e32 v25, v125
	v_mov_b32_e32 v24, v125
	v_mov_b32_e32 v23, v125
	v_mov_b32_e32 v22, v125
	v_mov_b32_e32 v21, v125
	v_mov_b32_e32 v20, v125
	v_mov_b32_e32 v19, v125
	v_mov_b32_e32 v18, v125
	v_mov_b32_e32 v9, v125
	v_mov_b32_e32 v8, v125
	v_mov_b32_e32 v7, v125
	v_mov_b32_e32 v6, v125
	v_mov_b32_e32 v5, v125
	v_mov_b32_e32 v4, v125
	v_mov_b32_e32 v3, v125
	v_mov_b32_e32 v2, v125
	s_cbranch_vccnz .LBB0_1203
	s_add_u32 s52, s52, 0x80
	s_addc_u32 s53, s53, 0
	s_add_u32 s75, s54, 0x100
	v_mov_b32_e32 v2, 0
	s_addc_u32 s76, s55, 0
	s_mov_b32 s54, 0
	v_mov_b32_e32 v3, v2
	v_mov_b32_e32 v4, v2
	v_mov_b32_e32 v5, v2
	v_mov_b32_e32 v6, v2
	v_mov_b32_e32 v7, v2
	v_mov_b32_e32 v8, v2
	v_mov_b32_e32 v9, v2
	v_mov_b32_e32 v18, v2
	v_mov_b32_e32 v19, v2
	v_mov_b32_e32 v20, v2
	v_mov_b32_e32 v21, v2
	v_mov_b32_e32 v22, v2
	v_mov_b32_e32 v23, v2
	v_mov_b32_e32 v24, v2
	v_mov_b32_e32 v25, v2
	v_mov_b32_e32 v34, v2
	v_mov_b32_e32 v35, v2
	v_mov_b32_e32 v36, v2
	v_mov_b32_e32 v37, v2
	v_mov_b32_e32 v38, v2
	v_mov_b32_e32 v39, v2
	v_mov_b32_e32 v40, v2
	v_mov_b32_e32 v41, v2
	v_mov_b32_e32 v50, v2
	v_mov_b32_e32 v51, v2
	v_mov_b32_e32 v52, v2
	v_mov_b32_e32 v53, v2
	v_mov_b32_e32 v54, v2
	v_mov_b32_e32 v55, v2
	v_mov_b32_e32 v56, v2
	v_mov_b32_e32 v57, v2
	v_mov_b32_e32 v10, v2
	v_mov_b32_e32 v11, v2
	v_mov_b32_e32 v12, v2
	v_mov_b32_e32 v13, v2
	v_mov_b32_e32 v14, v2
	v_mov_b32_e32 v15, v2
	v_mov_b32_e32 v16, v2
	v_mov_b32_e32 v17, v2
	v_mov_b32_e32 v26, v2
	v_mov_b32_e32 v27, v2
	v_mov_b32_e32 v28, v2
	v_mov_b32_e32 v29, v2
	v_mov_b32_e32 v30, v2
	v_mov_b32_e32 v31, v2
	v_mov_b32_e32 v32, v2
	v_mov_b32_e32 v33, v2
	v_mov_b32_e32 v42, v2
	v_mov_b32_e32 v43, v2
	v_mov_b32_e32 v44, v2
	v_mov_b32_e32 v45, v2
	v_mov_b32_e32 v46, v2
	v_mov_b32_e32 v47, v2
	v_mov_b32_e32 v48, v2
	v_mov_b32_e32 v49, v2
	v_mov_b32_e32 v58, v2
	v_mov_b32_e32 v59, v2
	v_mov_b32_e32 v60, v2
	v_mov_b32_e32 v61, v2
	v_mov_b32_e32 v62, v2
	v_mov_b32_e32 v63, v2
	v_mov_b32_e32 v64, v2
	v_mov_b32_e32 v65, v2
	v_mov_b32_e32 v66, v2
	v_mov_b32_e32 v67, v2
	v_mov_b32_e32 v68, v2
	v_mov_b32_e32 v69, v2
	v_mov_b32_e32 v70, v2
	v_mov_b32_e32 v71, v2
	v_mov_b32_e32 v72, v2
	v_mov_b32_e32 v73, v2
	v_mov_b32_e32 v82, v2
	v_mov_b32_e32 v83, v2
	v_mov_b32_e32 v84, v2
	v_mov_b32_e32 v85, v2
	v_mov_b32_e32 v86, v2
	v_mov_b32_e32 v87, v2
	v_mov_b32_e32 v88, v2
	v_mov_b32_e32 v89, v2
	v_mov_b32_e32 v98, v2
	v_mov_b32_e32 v99, v2
	v_mov_b32_e32 v100, v2
	v_mov_b32_e32 v101, v2
	v_mov_b32_e32 v102, v2
	v_mov_b32_e32 v103, v2
	v_mov_b32_e32 v104, v2
	v_mov_b32_e32 v105, v2
	v_mov_b32_e32 v114, v2
	v_mov_b32_e32 v115, v2
	v_mov_b32_e32 v116, v2
	v_mov_b32_e32 v117, v2
	v_mov_b32_e32 v118, v2
	v_mov_b32_e32 v119, v2
	v_mov_b32_e32 v120, v2
	v_mov_b32_e32 v121, v2
	v_mov_b32_e32 v74, v2
	v_mov_b32_e32 v75, v2
	v_mov_b32_e32 v76, v2
	v_mov_b32_e32 v77, v2
	v_mov_b32_e32 v78, v2
	v_mov_b32_e32 v79, v2
	v_mov_b32_e32 v80, v2
	v_mov_b32_e32 v81, v2
	v_mov_b32_e32 v90, v2
	v_mov_b32_e32 v91, v2
	v_mov_b32_e32 v92, v2
	v_mov_b32_e32 v93, v2
	v_mov_b32_e32 v94, v2
	v_mov_b32_e32 v95, v2
	v_mov_b32_e32 v96, v2
	v_mov_b32_e32 v97, v2
	v_mov_b32_e32 v106, v2
	v_mov_b32_e32 v107, v2
	v_mov_b32_e32 v108, v2
	v_mov_b32_e32 v109, v2
	v_mov_b32_e32 v110, v2
	v_mov_b32_e32 v111, v2
	v_mov_b32_e32 v112, v2
	v_mov_b32_e32 v113, v2
	v_mov_b32_e32 v126, v2
	v_mov_b32_e32 v127, v2
	v_mov_b32_e32 v128, v2
	v_mov_b32_e32 v129, v2
	v_mov_b32_e32 v122, v2
	v_mov_b32_e32 v123, v2
	v_mov_b32_e32 v124, v2
	v_mov_b32_e32 v125, v2
	.p2align	6

; template <class Epi, class Sched>
; __device__ __forceinline__ void gemm_phase(PG8_LAS unsigned char* lds, const Gemm g, const Sched& S, const Epi& E) {
;     ...
;         for (int t = 0; t < nt; t += 2) {
;             const bool last = (t == nt - 2);
;             const char* a1 = cA + (size_t)(t + 1) * kstep;
;             const char* a2 = last ? nA : cA + (size_t)(t + 2) * kstep; const char* b2 = last ? nB : cB + (size_t)(t + 2) * kstep;
;             const char* a3 = a2 + kstep; const char* b3 = b2 + kstep;
;     ...
; #pragma unroll
;         for (int a = 0; a < 2; ++a)
; #pragma unroll
;             for (int b = 0; b < 2; ++b)
; #pragma unroll
;                 for (int m = 0; m < 4; ++m)
; #pragma unroll
;                     for (int n = 0; n < 2; ++n) acc[a][b][m][n] = (f32x4){0.f, 0.f, 0.f, 0.f};
;         cur = nxt; cA = nA; cB = nB; ++ui;
.LBB0_1224:
	s_add_u32 s6, s56, 0x80
	s_addc_u32 s7, s57, 0
	s_add_u32 s56, s54, 0x100
	v_mov_b32_e32 v2, 0
	s_addc_u32 s57, s55, 0
	s_mov_b32 s54, 0
	v_mov_b32_e32 v3, v2
	v_mov_b32_e32 v4, v2
	v_mov_b32_e32 v5, v2
	v_mov_b32_e32 v6, v2
	v_mov_b32_e32 v7, v2
	v_mov_b32_e32 v8, v2
	v_mov_b32_e32 v9, v2
	v_mov_b32_e32 v18, v2
	v_mov_b32_e32 v19, v2
	v_mov_b32_e32 v20, v2
	v_mov_b32_e32 v21, v2
	v_mov_b32_e32 v22, v2
	v_mov_b32_e32 v23, v2
	v_mov_b32_e32 v24, v2
	v_mov_b32_e32 v25, v2
	v_mov_b32_e32 v34, v2
	v_mov_b32_e32 v35, v2
	v_mov_b32_e32 v36, v2
	v_mov_b32_e32 v37, v2
	v_mov_b32_e32 v38, v2
	v_mov_b32_e32 v39, v2
	v_mov_b32_e32 v40, v2
	v_mov_b32_e32 v41, v2
	v_mov_b32_e32 v50, v2
	v_mov_b32_e32 v51, v2
	v_mov_b32_e32 v52, v2
	v_mov_b32_e32 v53, v2
	v_mov_b32_e32 v54, v2
	v_mov_b32_e32 v55, v2
	v_mov_b32_e32 v56, v2
	v_mov_b32_e32 v57, v2
	v_mov_b32_e32 v10, v2
	v_mov_b32_e32 v11, v2
	v_mov_b32_e32 v12, v2
	v_mov_b32_e32 v13, v2
	v_mov_b32_e32 v14, v2
	v_mov_b32_e32 v15, v2
	v_mov_b32_e32 v16, v2
	v_mov_b32_e32 v17, v2
	v_mov_b32_e32 v26, v2
	v_mov_b32_e32 v27, v2
	v_mov_b32_e32 v28, v2
	v_mov_b32_e32 v29, v2
	v_mov_b32_e32 v30, v2
	v_mov_b32_e32 v31, v2
	v_mov_b32_e32 v32, v2
	v_mov_b32_e32 v33, v2
	v_mov_b32_e32 v42, v2
	v_mov_b32_e32 v43, v2
	v_mov_b32_e32 v44, v2
	v_mov_b32_e32 v45, v2
	v_mov_b32_e32 v46, v2
	v_mov_b32_e32 v47, v2
	v_mov_b32_e32 v48, v2
	v_mov_b32_e32 v49, v2
	v_mov_b32_e32 v58, v2
	v_mov_b32_e32 v59, v2
	v_mov_b32_e32 v60, v2
	v_mov_b32_e32 v61, v2
	v_mov_b32_e32 v62, v2
	v_mov_b32_e32 v63, v2
	v_mov_b32_e32 v64, v2
	v_mov_b32_e32 v65, v2
	v_mov_b32_e32 v66, v2
	v_mov_b32_e32 v67, v2
	v_mov_b32_e32 v68, v2
	v_mov_b32_e32 v69, v2
	v_mov_b32_e32 v70, v2
	v_mov_b32_e32 v71, v2
	v_mov_b32_e32 v72, v2
	v_mov_b32_e32 v73, v2
	v_mov_b32_e32 v82, v2
	v_mov_b32_e32 v83, v2
	v_mov_b32_e32 v84, v2
	v_mov_b32_e32 v85, v2
	v_mov_b32_e32 v86, v2
	v_mov_b32_e32 v87, v2
	v_mov_b32_e32 v88, v2
	v_mov_b32_e32 v89, v2
	v_mov_b32_e32 v98, v2
	v_mov_b32_e32 v99, v2
	v_mov_b32_e32 v100, v2
	v_mov_b32_e32 v101, v2
	v_mov_b32_e32 v102, v2
	v_mov_b32_e32 v103, v2
	v_mov_b32_e32 v104, v2
	v_mov_b32_e32 v105, v2
	v_mov_b32_e32 v114, v2
	v_mov_b32_e32 v115, v2
	v_mov_b32_e32 v116, v2
	v_mov_b32_e32 v117, v2
	v_mov_b32_e32 v118, v2
	v_mov_b32_e32 v119, v2
	v_mov_b32_e32 v120, v2
	v_mov_b32_e32 v121, v2
	v_mov_b32_e32 v74, v2
	v_mov_b32_e32 v75, v2
	v_mov_b32_e32 v76, v2
	v_mov_b32_e32 v77, v2
	v_mov_b32_e32 v78, v2
	v_mov_b32_e32 v79, v2
	v_mov_b32_e32 v80, v2
	v_mov_b32_e32 v81, v2
	v_mov_b32_e32 v90, v2
	v_mov_b32_e32 v91, v2
	v_mov_b32_e32 v92, v2
	v_mov_b32_e32 v93, v2
	v_mov_b32_e32 v94, v2
	v_mov_b32_e32 v95, v2
	v_mov_b32_e32 v96, v2
	v_mov_b32_e32 v97, v2
	v_mov_b32_e32 v106, v2
	v_mov_b32_e32 v107, v2
	v_mov_b32_e32 v108, v2
	v_mov_b32_e32 v109, v2
	v_mov_b32_e32 v110, v2
	v_mov_b32_e32 v111, v2
	v_mov_b32_e32 v112, v2
	v_mov_b32_e32 v113, v2
	v_mov_b32_e32 v122, v2
	v_mov_b32_e32 v123, v2
	v_mov_b32_e32 v124, v2
	v_mov_b32_e32 v125, v2
	v_mov_b32_e32 v126, v2
	v_mov_b32_e32 v127, v2
	v_mov_b32_e32 v128, v2
	v_mov_b32_e32 v129, v2
	.p2align	6

; template <class Epi, class Sched>
; __device__ __forceinline__ void gemm_phase(PG8_LAS unsigned char* lds, const Gemm g, const Sched& S, const Epi& E) {
;     ...
;         for (int t = 0; t < nt; t += 2) {
;             const bool last = (t == nt - 2);
;             const char* a1 = cA + (size_t)(t + 1) * kstep;
;             const char* a2 = last ? nA : cA + (size_t)(t + 2) * kstep; const char* b2 = last ? nB : cB + (size_t)(t + 2) * kstep;
;             const char* a3 = a2 + kstep; const char* b3 = b2 + kstep;
;     ...
; #pragma unroll
;         for (int a = 0; a < 2; ++a)
; #pragma unroll
;             for (int b = 0; b < 2; ++b)
; #pragma unroll
;                 for (int m = 0; m < 4; ++m)
; #pragma unroll
;                     for (int n = 0; n < 2; ++n) acc[a][b][m][n] = (f32x4){0.f, 0.f, 0.f, 0.f};
;         cur = nxt; cA = nA; cB = nB; ++ui;
.LBB0_1283:
	v_mov_b32_e32 v125, 0
	s_andn2_b64 vcc, exec, s[26:27]
	v_mov_b32_e32 v124, v125
	v_mov_b32_e32 v123, v125
	v_mov_b32_e32 v122, v125
	v_mov_b32_e32 v129, v125
	v_mov_b32_e32 v128, v125
	v_mov_b32_e32 v127, v125
	v_mov_b32_e32 v126, v125
	v_mov_b32_e32 v113, v125
	v_mov_b32_e32 v112, v125
	v_mov_b32_e32 v111, v125
	v_mov_b32_e32 v110, v125
	v_mov_b32_e32 v109, v125
	v_mov_b32_e32 v108, v125
	v_mov_b32_e32 v107, v125
	v_mov_b32_e32 v106, v125
	v_mov_b32_e32 v97, v125
	v_mov_b32_e32 v96, v125
	v_mov_b32_e32 v95, v125
	v_mov_b32_e32 v94, v125
	v_mov_b32_e32 v93, v125
	v_mov_b32_e32 v92, v125
	v_mov_b32_e32 v91, v125
	v_mov_b32_e32 v90, v125
	v_mov_b32_e32 v81, v125
	v_mov_b32_e32 v80, v125
	v_mov_b32_e32 v79, v125
	v_mov_b32_e32 v78, v125
	v_mov_b32_e32 v77, v125
	v_mov_b32_e32 v76, v125
	v_mov_b32_e32 v75, v125
	v_mov_b32_e32 v74, v125
	v_mov_b32_e32 v121, v125
	v_mov_b32_e32 v120, v125
	v_mov_b32_e32 v119, v125
	v_mov_b32_e32 v118, v125
	v_mov_b32_e32 v117, v125
	v_mov_b32_e32 v116, v125
	v_mov_b32_e32 v115, v125
	v_mov_b32_e32 v114, v125
	v_mov_b32_e32 v105, v125
	v_mov_b32_e32 v104, v125
	v_mov_b32_e32 v103, v125
	v_mov_b32_e32 v102, v125
	v_mov_b32_e32 v101, v125
	v_mov_b32_e32 v100, v125
	v_mov_b32_e32 v99, v125
	v_mov_b32_e32 v98, v125
	v_mov_b32_e32 v89, v125
	v_mov_b32_e32 v88, v125
	v_mov_b32_e32 v87, v125
	v_mov_b32_e32 v86, v125
	v_mov_b32_e32 v85, v125
	v_mov_b32_e32 v84, v125
	v_mov_b32_e32 v83, v125
	v_mov_b32_e32 v82, v125
	v_mov_b32_e32 v73, v125
	v_mov_b32_e32 v72, v125
	v_mov_b32_e32 v71, v125
	v_mov_b32_e32 v70, v125
	v_mov_b32_e32 v69, v125
	v_mov_b32_e32 v68, v125
	v_mov_b32_e32 v67, v125
	v_mov_b32_e32 v66, v125
	v_mov_b32_e32 v65, v125
	v_mov_b32_e32 v64, v125
	v_mov_b32_e32 v63, v125
	v_mov_b32_e32 v62, v125
	v_mov_b32_e32 v61, v125
	v_mov_b32_e32 v60, v125
	v_mov_b32_e32 v59, v125
	v_mov_b32_e32 v58, v125
	v_mov_b32_e32 v49, v125
	v_mov_b32_e32 v48, v125
	v_mov_b32_e32 v47, v125
	v_mov_b32_e32 v46, v125
	v_mov_b32_e32 v45, v125
	v_mov_b32_e32 v44, v125
	v_mov_b32_e32 v43, v125
	v_mov_b32_e32 v42, v125
	v_mov_b32_e32 v33, v125
	v_mov_b32_e32 v32, v125
	v_mov_b32_e32 v31, v125
	v_mov_b32_e32 v30, v125
	v_mov_b32_e32 v29, v125
	v_mov_b32_e32 v28, v125
	v_mov_b32_e32 v27, v125
	v_mov_b32_e32 v26, v125
	v_mov_b32_e32 v17, v125
	v_mov_b32_e32 v16, v125
	v_mov_b32_e32 v15, v125
	v_mov_b32_e32 v14, v125
	v_mov_b32_e32 v13, v125
	v_mov_b32_e32 v12, v125
	v_mov_b32_e32 v11, v125
	v_mov_b32_e32 v10, v125
	v_mov_b32_e32 v57, v125
	v_mov_b32_e32 v56, v125
	v_mov_b32_e32 v55, v125
	v_mov_b32_e32 v54, v125
	v_mov_b32_e32 v53, v125
	v_mov_b32_e32 v52, v125
	v_mov_b32_e32 v51, v125
	v_mov_b32_e32 v50, v125
	v_mov_b32_e32 v41, v125
	v_mov_b32_e32 v40, v125
	v_mov_b32_e32 v39, v125
	v_mov_b32_e32 v38, v125
	v_mov_b32_e32 v37, v125
	v_mov_b32_e32 v36, v125
	v_mov_b32_e32 v35, v125
	v_mov_b32_e32 v34, v125
	v_mov_b32_e32 v25, v125
	v_mov_b32_e32 v24, v125
	v_mov_b32_e32 v23, v125
	v_mov_b32_e32 v22, v125
	v_mov_b32_e32 v21, v125
	v_mov_b32_e32 v20, v125
	v_mov_b32_e32 v19, v125
	v_mov_b32_e32 v18, v125
	v_mov_b32_e32 v9, v125
	v_mov_b32_e32 v8, v125
	v_mov_b32_e32 v7, v125
	v_mov_b32_e32 v6, v125
	v_mov_b32_e32 v5, v125
	v_mov_b32_e32 v4, v125
	v_mov_b32_e32 v3, v125
	v_mov_b32_e32 v2, v125
	s_cbranch_vccnz .LBB0_1287
	s_add_u32 s42, s42, 0x80
	s_addc_u32 s43, s43, 0
	s_add_u32 s70, s44, 0x100
	v_mov_b32_e32 v2, 0
	s_addc_u32 s71, s45, 0
	s_mov_b32 s44, 0
	v_mov_b32_e32 v3, v2
	v_mov_b32_e32 v4, v2
	v_mov_b32_e32 v5, v2
	v_mov_b32_e32 v6, v2
	v_mov_b32_e32 v7, v2
	v_mov_b32_e32 v8, v2
	v_mov_b32_e32 v9, v2
	v_mov_b32_e32 v18, v2
	v_mov_b32_e32 v19, v2
	v_mov_b32_e32 v20, v2
	v_mov_b32_e32 v21, v2
	v_mov_b32_e32 v22, v2
	v_mov_b32_e32 v23, v2
	v_mov_b32_e32 v24, v2
	v_mov_b32_e32 v25, v2
	v_mov_b32_e32 v34, v2
	v_mov_b32_e32 v35, v2
	v_mov_b32_e32 v36, v2
	v_mov_b32_e32 v37, v2
	v_mov_b32_e32 v38, v2
	v_mov_b32_e32 v39, v2
	v_mov_b32_e32 v40, v2
	v_mov_b32_e32 v41, v2
	v_mov_b32_e32 v50, v2
	v_mov_b32_e32 v51, v2
	v_mov_b32_e32 v52, v2
	v_mov_b32_e32 v53, v2
	v_mov_b32_e32 v54, v2
	v_mov_b32_e32 v55, v2
	v_mov_b32_e32 v56, v2
	v_mov_b32_e32 v57, v2
	v_mov_b32_e32 v10, v2
	v_mov_b32_e32 v11, v2
	v_mov_b32_e32 v12, v2
	v_mov_b32_e32 v13, v2
	v_mov_b32_e32 v14, v2
	v_mov_b32_e32 v15, v2
	v_mov_b32_e32 v16, v2
	v_mov_b32_e32 v17, v2
	v_mov_b32_e32 v26, v2
	v_mov_b32_e32 v27, v2
	v_mov_b32_e32 v28, v2
	v_mov_b32_e32 v29, v2
	v_mov_b32_e32 v30, v2
	v_mov_b32_e32 v31, v2
	v_mov_b32_e32 v32, v2
	v_mov_b32_e32 v33, v2
	v_mov_b32_e32 v42, v2
	v_mov_b32_e32 v43, v2
	v_mov_b32_e32 v44, v2
	v_mov_b32_e32 v45, v2
	v_mov_b32_e32 v46, v2
	v_mov_b32_e32 v47, v2
	v_mov_b32_e32 v48, v2
	v_mov_b32_e32 v49, v2
	v_mov_b32_e32 v58, v2
	v_mov_b32_e32 v59, v2
	v_mov_b32_e32 v60, v2
	v_mov_b32_e32 v61, v2
	v_mov_b32_e32 v62, v2
	v_mov_b32_e32 v63, v2
	v_mov_b32_e32 v64, v2
	v_mov_b32_e32 v65, v2
	v_mov_b32_e32 v66, v2
	v_mov_b32_e32 v67, v2
	v_mov_b32_e32 v68, v2
	v_mov_b32_e32 v69, v2
	v_mov_b32_e32 v70, v2
	v_mov_b32_e32 v71, v2
	v_mov_b32_e32 v72, v2
	v_mov_b32_e32 v73, v2
	v_mov_b32_e32 v82, v2
	v_mov_b32_e32 v83, v2
	v_mov_b32_e32 v84, v2
	v_mov_b32_e32 v85, v2
	v_mov_b32_e32 v86, v2
	v_mov_b32_e32 v87, v2
	v_mov_b32_e32 v88, v2
	v_mov_b32_e32 v89, v2
	v_mov_b32_e32 v98, v2
	v_mov_b32_e32 v99, v2
	v_mov_b32_e32 v100, v2
	v_mov_b32_e32 v101, v2
	v_mov_b32_e32 v102, v2
	v_mov_b32_e32 v103, v2
	v_mov_b32_e32 v104, v2
	v_mov_b32_e32 v105, v2
	v_mov_b32_e32 v114, v2
	v_mov_b32_e32 v115, v2
	v_mov_b32_e32 v116, v2
	v_mov_b32_e32 v117, v2
	v_mov_b32_e32 v118, v2
	v_mov_b32_e32 v119, v2
	v_mov_b32_e32 v120, v2
	v_mov_b32_e32 v121, v2
	v_mov_b32_e32 v74, v2
	v_mov_b32_e32 v75, v2
	v_mov_b32_e32 v76, v2
	v_mov_b32_e32 v77, v2
	v_mov_b32_e32 v78, v2
	v_mov_b32_e32 v79, v2
	v_mov_b32_e32 v80, v2
	v_mov_b32_e32 v81, v2
	v_mov_b32_e32 v90, v2
	v_mov_b32_e32 v91, v2
	v_mov_b32_e32 v92, v2
	v_mov_b32_e32 v93, v2
	v_mov_b32_e32 v94, v2
	v_mov_b32_e32 v95, v2
	v_mov_b32_e32 v96, v2
	v_mov_b32_e32 v97, v2
	v_mov_b32_e32 v106, v2
	v_mov_b32_e32 v107, v2
	v_mov_b32_e32 v108, v2
	v_mov_b32_e32 v109, v2
	v_mov_b32_e32 v110, v2
	v_mov_b32_e32 v111, v2
	v_mov_b32_e32 v112, v2
	v_mov_b32_e32 v113, v2
	v_mov_b32_e32 v126, v2
	v_mov_b32_e32 v127, v2
	v_mov_b32_e32 v128, v2
	v_mov_b32_e32 v129, v2
	v_mov_b32_e32 v122, v2
	v_mov_b32_e32 v123, v2
	v_mov_b32_e32 v124, v2
	v_mov_b32_e32 v125, v2
	.p2align	6

; template <class Epi, class Sched>
; __device__ __forceinline__ void gemm_phase(PG8_LAS unsigned char* lds, const Gemm g, const Sched& S, const Epi& E) {
;     ...
;         for (int t = 0; t < nt; t += 2) {
;             const bool last = (t == nt - 2);
;             const char* a1 = cA + (size_t)(t + 1) * kstep;
;             const char* a2 = last ? nA : cA + (size_t)(t + 2) * kstep; const char* b2 = last ? nB : cB + (size_t)(t + 2) * kstep;
;             const char* a3 = a2 + kstep; const char* b3 = b2 + kstep;
;     ...
; #pragma unroll
;         for (int a = 0; a < 2; ++a)
; #pragma unroll
;             for (int b = 0; b < 2; ++b)
; #pragma unroll
;                 for (int m = 0; m < 4; ++m)
; #pragma unroll
;                     for (int n = 0; n < 2; ++n) acc[a][b][m][n] = (f32x4){0.f, 0.f, 0.f, 0.f};
;         cur = nxt; cA = nA; cB = nB; ++ui;
.LBB0_1361:
	v_mov_b32_e32 v181, 0
	s_andn2_b64 vcc, exec, s[26:27]
	v_mov_b32_e32 v180, v181
	v_mov_b32_e32 v179, v181
	v_mov_b32_e32 v178, v181
	v_mov_b32_e32 v185, v181
	v_mov_b32_e32 v184, v181
	v_mov_b32_e32 v183, v181
	v_mov_b32_e32 v182, v181
	v_mov_b32_e32 v145, v181
	v_mov_b32_e32 v144, v181
	v_mov_b32_e32 v143, v181
	v_mov_b32_e32 v142, v181
	v_mov_b32_e32 v141, v181
	v_mov_b32_e32 v140, v181
	v_mov_b32_e32 v139, v181
	v_mov_b32_e32 v138, v181
	v_mov_b32_e32 v105, v181
	v_mov_b32_e32 v104, v181
	v_mov_b32_e32 v103, v181
	v_mov_b32_e32 v102, v181
	v_mov_b32_e32 v101, v181
	v_mov_b32_e32 v100, v181
	v_mov_b32_e32 v99, v181
	v_mov_b32_e32 v98, v181
	v_mov_b32_e32 v81, v181
	v_mov_b32_e32 v80, v181
	v_mov_b32_e32 v79, v181
	v_mov_b32_e32 v78, v181
	v_mov_b32_e32 v77, v181
	v_mov_b32_e32 v76, v181
	v_mov_b32_e32 v75, v181
	v_mov_b32_e32 v74, v181
	v_mov_b32_e32 v161, v181
	v_mov_b32_e32 v160, v181
	v_mov_b32_e32 v159, v181
	v_mov_b32_e32 v158, v181
	v_mov_b32_e32 v157, v181
	v_mov_b32_e32 v156, v181
	v_mov_b32_e32 v155, v181
	v_mov_b32_e32 v154, v181
	v_mov_b32_e32 v129, v181
	v_mov_b32_e32 v128, v181
	v_mov_b32_e32 v127, v181
	v_mov_b32_e32 v126, v181
	v_mov_b32_e32 v125, v181
	v_mov_b32_e32 v124, v181
	v_mov_b32_e32 v123, v181
	v_mov_b32_e32 v122, v181
	v_mov_b32_e32 v89, v181
	v_mov_b32_e32 v88, v181
	v_mov_b32_e32 v87, v181
	v_mov_b32_e32 v86, v181
	v_mov_b32_e32 v85, v181
	v_mov_b32_e32 v84, v181
	v_mov_b32_e32 v83, v181
	v_mov_b32_e32 v82, v181
	v_mov_b32_e32 v73, v181
	v_mov_b32_e32 v72, v181
	v_mov_b32_e32 v71, v181
	v_mov_b32_e32 v70, v181
	v_mov_b32_e32 v69, v181
	v_mov_b32_e32 v68, v181
	v_mov_b32_e32 v67, v181
	v_mov_b32_e32 v66, v181
	v_mov_b32_e32 v65, v181
	v_mov_b32_e32 v64, v181
	v_mov_b32_e32 v63, v181
	v_mov_b32_e32 v62, v181
	v_mov_b32_e32 v61, v181
	v_mov_b32_e32 v60, v181
	v_mov_b32_e32 v59, v181
	v_mov_b32_e32 v58, v181
	v_mov_b32_e32 v49, v181
	v_mov_b32_e32 v48, v181
	v_mov_b32_e32 v47, v181
	v_mov_b32_e32 v46, v181
	v_mov_b32_e32 v45, v181
	v_mov_b32_e32 v44, v181
	v_mov_b32_e32 v43, v181
	v_mov_b32_e32 v42, v181
	v_mov_b32_e32 v33, v181
	v_mov_b32_e32 v32, v181
	v_mov_b32_e32 v31, v181
	v_mov_b32_e32 v30, v181
	v_mov_b32_e32 v29, v181
	v_mov_b32_e32 v28, v181
	v_mov_b32_e32 v27, v181
	v_mov_b32_e32 v26, v181
	v_mov_b32_e32 v17, v181
	v_mov_b32_e32 v16, v181
	v_mov_b32_e32 v15, v181
	v_mov_b32_e32 v14, v181
	v_mov_b32_e32 v13, v181
	v_mov_b32_e32 v12, v181
	v_mov_b32_e32 v11, v181
	v_mov_b32_e32 v10, v181
	v_mov_b32_e32 v57, v181
	v_mov_b32_e32 v56, v181
	v_mov_b32_e32 v55, v181
	v_mov_b32_e32 v54, v181
	v_mov_b32_e32 v53, v181
	v_mov_b32_e32 v52, v181
	v_mov_b32_e32 v51, v181
	v_mov_b32_e32 v50, v181
	v_mov_b32_e32 v41, v181
	v_mov_b32_e32 v40, v181
	v_mov_b32_e32 v39, v181
	v_mov_b32_e32 v38, v181
	v_mov_b32_e32 v37, v181
	v_mov_b32_e32 v36, v181
	v_mov_b32_e32 v35, v181
	v_mov_b32_e32 v34, v181
	v_mov_b32_e32 v25, v181
	v_mov_b32_e32 v24, v181
	v_mov_b32_e32 v23, v181
	v_mov_b32_e32 v22, v181
	v_mov_b32_e32 v21, v181
	v_mov_b32_e32 v20, v181
	v_mov_b32_e32 v19, v181
	v_mov_b32_e32 v18, v181
	v_mov_b32_e32 v9, v181
	v_mov_b32_e32 v8, v181
	v_mov_b32_e32 v7, v181
	v_mov_b32_e32 v6, v181
	v_mov_b32_e32 v5, v181
	v_mov_b32_e32 v4, v181
	v_mov_b32_e32 v3, v181
	v_mov_b32_e32 v2, v181
	s_cbranch_vccnz .LBB0_1364
	s_add_u32 s4, s52, 0x80
	s_addc_u32 s5, s53, 0
	s_add_u32 s52, s50, 0x100
	v_mov_b32_e32 v2, 0
	s_addc_u32 s53, s51, 0
	s_mov_b32 s50, 0
	v_mov_b32_e32 v3, v2
	v_mov_b32_e32 v4, v2
	v_mov_b32_e32 v5, v2
	v_mov_b32_e32 v6, v2
	v_mov_b32_e32 v7, v2
	v_mov_b32_e32 v8, v2
	v_mov_b32_e32 v9, v2
	v_mov_b32_e32 v18, v2
	v_mov_b32_e32 v19, v2
	v_mov_b32_e32 v20, v2
	v_mov_b32_e32 v21, v2
	v_mov_b32_e32 v22, v2
	v_mov_b32_e32 v23, v2
	v_mov_b32_e32 v24, v2
	v_mov_b32_e32 v25, v2
	v_mov_b32_e32 v34, v2
	v_mov_b32_e32 v35, v2
	v_mov_b32_e32 v36, v2
	v_mov_b32_e32 v37, v2
	v_mov_b32_e32 v38, v2
	v_mov_b32_e32 v39, v2
	v_mov_b32_e32 v40, v2
	v_mov_b32_e32 v41, v2
	v_mov_b32_e32 v50, v2
	v_mov_b32_e32 v51, v2
	v_mov_b32_e32 v52, v2
	v_mov_b32_e32 v53, v2
	v_mov_b32_e32 v54, v2
	v_mov_b32_e32 v55, v2
	v_mov_b32_e32 v56, v2
	v_mov_b32_e32 v57, v2
	v_mov_b32_e32 v10, v2
	v_mov_b32_e32 v11, v2
	v_mov_b32_e32 v12, v2
	v_mov_b32_e32 v13, v2
	v_mov_b32_e32 v14, v2
	v_mov_b32_e32 v15, v2
	v_mov_b32_e32 v16, v2
	v_mov_b32_e32 v17, v2
	v_mov_b32_e32 v26, v2
	v_mov_b32_e32 v27, v2
	v_mov_b32_e32 v28, v2
	v_mov_b32_e32 v29, v2
	v_mov_b32_e32 v30, v2
	v_mov_b32_e32 v31, v2
	v_mov_b32_e32 v32, v2
	v_mov_b32_e32 v33, v2
	v_mov_b32_e32 v42, v2
	v_mov_b32_e32 v43, v2
	v_mov_b32_e32 v44, v2
	v_mov_b32_e32 v45, v2
	v_mov_b32_e32 v46, v2
	v_mov_b32_e32 v47, v2
	v_mov_b32_e32 v48, v2
	v_mov_b32_e32 v49, v2
	v_mov_b32_e32 v58, v2
	v_mov_b32_e32 v59, v2
	v_mov_b32_e32 v60, v2
	v_mov_b32_e32 v61, v2
	v_mov_b32_e32 v62, v2
	v_mov_b32_e32 v63, v2
	v_mov_b32_e32 v64, v2
	v_mov_b32_e32 v65, v2
	v_mov_b32_e32 v66, v2
	v_mov_b32_e32 v67, v2
	v_mov_b32_e32 v68, v2
	v_mov_b32_e32 v69, v2
	v_mov_b32_e32 v70, v2
	v_mov_b32_e32 v71, v2
	v_mov_b32_e32 v72, v2
	v_mov_b32_e32 v73, v2
	v_mov_b32_e32 v82, v2
	v_mov_b32_e32 v83, v2
	v_mov_b32_e32 v84, v2
	v_mov_b32_e32 v85, v2
	v_mov_b32_e32 v86, v2
	v_mov_b32_e32 v87, v2
	v_mov_b32_e32 v88, v2
	v_mov_b32_e32 v89, v2
	v_mov_b32_e32 v122, v2
	v_mov_b32_e32 v123, v2
	v_mov_b32_e32 v124, v2
	v_mov_b32_e32 v125, v2
	v_mov_b32_e32 v126, v2
	v_mov_b32_e32 v127, v2
	v_mov_b32_e32 v128, v2
	v_mov_b32_e32 v129, v2
	v_mov_b32_e32 v154, v2
	v_mov_b32_e32 v155, v2
	v_mov_b32_e32 v156, v2
	v_mov_b32_e32 v157, v2
	v_mov_b32_e32 v158, v2
	v_mov_b32_e32 v159, v2
	v_mov_b32_e32 v160, v2
	v_mov_b32_e32 v161, v2
	v_mov_b32_e32 v74, v2
	v_mov_b32_e32 v75, v2
	v_mov_b32_e32 v76, v2
	v_mov_b32_e32 v77, v2
	v_mov_b32_e32 v78, v2
	v_mov_b32_e32 v79, v2
	v_mov_b32_e32 v80, v2
	v_mov_b32_e32 v81, v2
	v_mov_b32_e32 v98, v2
	v_mov_b32_e32 v99, v2
	v_mov_b32_e32 v100, v2
	v_mov_b32_e32 v101, v2
	v_mov_b32_e32 v102, v2
	v_mov_b32_e32 v103, v2
	v_mov_b32_e32 v104, v2
	v_mov_b32_e32 v105, v2
	v_mov_b32_e32 v138, v2
	v_mov_b32_e32 v139, v2
	v_mov_b32_e32 v140, v2
	v_mov_b32_e32 v141, v2
	v_mov_b32_e32 v142, v2
	v_mov_b32_e32 v143, v2
	v_mov_b32_e32 v144, v2
	v_mov_b32_e32 v145, v2
	v_mov_b32_e32 v182, v2
	v_mov_b32_e32 v183, v2
	v_mov_b32_e32 v184, v2
	v_mov_b32_e32 v185, v2
	v_mov_b32_e32 v178, v2
	v_mov_b32_e32 v179, v2
	v_mov_b32_e32 v180, v2
	v_mov_b32_e32 v181, v2
	.p2align	6

; template <class Epi, class Sched>
; __device__ __forceinline__ void gemm_phase(PG8_LAS unsigned char* lds, const Gemm g, const Sched& S, const Epi& E) {
;     ...
;         for (int t = 0; t < nt; t += 2) {
;             const bool last = (t == nt - 2);
;             const char* a1 = cA + (size_t)(t + 1) * kstep;
;             const char* a2 = last ? nA : cA + (size_t)(t + 2) * kstep; const char* b2 = last ? nB : cB + (size_t)(t + 2) * kstep;
;             const char* a3 = a2 + kstep; const char* b3 = b2 + kstep;
;     ...
; #pragma unroll
;         for (int a = 0; a < 2; ++a)
; #pragma unroll
;             for (int b = 0; b < 2; ++b)
; #pragma unroll
;                 for (int m = 0; m < 4; ++m)
; #pragma unroll
;                     for (int n = 0; n < 2; ++n) acc[a][b][m][n] = (f32x4){0.f, 0.f, 0.f, 0.f};
;         cur = nxt; cA = nA; cB = nB; ++ui;
.LBB0_1473:
	v_mov_b32_e32 v129, 0
	s_andn2_b64 vcc, exec, s[42:43]
	v_mov_b32_e32 v128, v129
	v_mov_b32_e32 v127, v129
	v_mov_b32_e32 v126, v129
	v_mov_b32_e32 v125, v129
	v_mov_b32_e32 v124, v129
	v_mov_b32_e32 v123, v129
	v_mov_b32_e32 v122, v129
	v_mov_b32_e32 v113, v129
	v_mov_b32_e32 v112, v129
	v_mov_b32_e32 v111, v129
	v_mov_b32_e32 v110, v129
	v_mov_b32_e32 v109, v129
	v_mov_b32_e32 v108, v129
	v_mov_b32_e32 v107, v129
	v_mov_b32_e32 v106, v129
	v_mov_b32_e32 v97, v129
	v_mov_b32_e32 v96, v129
	v_mov_b32_e32 v95, v129
	v_mov_b32_e32 v94, v129
	v_mov_b32_e32 v93, v129
	v_mov_b32_e32 v92, v129
	v_mov_b32_e32 v91, v129
	v_mov_b32_e32 v90, v129
	v_mov_b32_e32 v81, v129
	v_mov_b32_e32 v80, v129
	v_mov_b32_e32 v79, v129
	v_mov_b32_e32 v78, v129
	v_mov_b32_e32 v77, v129
	v_mov_b32_e32 v76, v129
	v_mov_b32_e32 v75, v129
	v_mov_b32_e32 v74, v129
	v_mov_b32_e32 v121, v129
	v_mov_b32_e32 v120, v129
	v_mov_b32_e32 v119, v129
	v_mov_b32_e32 v118, v129
	v_mov_b32_e32 v117, v129
	v_mov_b32_e32 v116, v129
	v_mov_b32_e32 v115, v129
	v_mov_b32_e32 v114, v129
	v_mov_b32_e32 v105, v129
	v_mov_b32_e32 v104, v129
	v_mov_b32_e32 v103, v129
	v_mov_b32_e32 v102, v129
	v_mov_b32_e32 v101, v129
	v_mov_b32_e32 v100, v129
	v_mov_b32_e32 v99, v129
	v_mov_b32_e32 v98, v129
	v_mov_b32_e32 v89, v129
	v_mov_b32_e32 v88, v129
	v_mov_b32_e32 v87, v129
	v_mov_b32_e32 v86, v129
	v_mov_b32_e32 v85, v129
	v_mov_b32_e32 v84, v129
	v_mov_b32_e32 v83, v129
	v_mov_b32_e32 v82, v129
	v_mov_b32_e32 v73, v129
	v_mov_b32_e32 v72, v129
	v_mov_b32_e32 v71, v129
	v_mov_b32_e32 v70, v129
	v_mov_b32_e32 v69, v129
	v_mov_b32_e32 v68, v129
	v_mov_b32_e32 v67, v129
	v_mov_b32_e32 v66, v129
	v_mov_b32_e32 v65, v129
	v_mov_b32_e32 v64, v129
	v_mov_b32_e32 v63, v129
	v_mov_b32_e32 v62, v129
	v_mov_b32_e32 v61, v129
	v_mov_b32_e32 v60, v129
	v_mov_b32_e32 v59, v129
	v_mov_b32_e32 v58, v129
	v_mov_b32_e32 v49, v129
	v_mov_b32_e32 v48, v129
	v_mov_b32_e32 v47, v129
	v_mov_b32_e32 v46, v129
	v_mov_b32_e32 v45, v129
	v_mov_b32_e32 v44, v129
	v_mov_b32_e32 v43, v129
	v_mov_b32_e32 v42, v129
	v_mov_b32_e32 v33, v129
	v_mov_b32_e32 v32, v129
	v_mov_b32_e32 v31, v129
	v_mov_b32_e32 v30, v129
	v_mov_b32_e32 v29, v129
	v_mov_b32_e32 v28, v129
	v_mov_b32_e32 v27, v129
	v_mov_b32_e32 v26, v129
	v_mov_b32_e32 v17, v129
	v_mov_b32_e32 v16, v129
	v_mov_b32_e32 v15, v129
	v_mov_b32_e32 v14, v129
	v_mov_b32_e32 v13, v129
	v_mov_b32_e32 v12, v129
	v_mov_b32_e32 v11, v129
	v_mov_b32_e32 v10, v129
	v_mov_b32_e32 v57, v129
	v_mov_b32_e32 v56, v129
	v_mov_b32_e32 v55, v129
	v_mov_b32_e32 v54, v129
	v_mov_b32_e32 v53, v129
	v_mov_b32_e32 v52, v129
	v_mov_b32_e32 v51, v129
	v_mov_b32_e32 v50, v129
	v_mov_b32_e32 v41, v129
	v_mov_b32_e32 v40, v129
	v_mov_b32_e32 v39, v129
	v_mov_b32_e32 v38, v129
	v_mov_b32_e32 v37, v129
	v_mov_b32_e32 v36, v129
	v_mov_b32_e32 v35, v129
	v_mov_b32_e32 v34, v129
	v_mov_b32_e32 v25, v129
	v_mov_b32_e32 v24, v129
	v_mov_b32_e32 v23, v129
	v_mov_b32_e32 v22, v129
	v_mov_b32_e32 v21, v129
	v_mov_b32_e32 v20, v129
	v_mov_b32_e32 v19, v129
	v_mov_b32_e32 v18, v129
	v_mov_b32_e32 v9, v129
	v_mov_b32_e32 v8, v129
	v_mov_b32_e32 v7, v129
	v_mov_b32_e32 v6, v129
	s_waitcnt lgkmcnt(0)
	v_mov_b32_e32 v5, v129
	v_mov_b32_e32 v4, v129
	v_mov_b32_e32 v3, v129
	v_mov_b32_e32 v2, v129
	s_cbranch_vccnz .LBB0_1476
	s_add_u32 s52, s52, 0x80
	s_addc_u32 s53, s53, 0
	s_add_u32 s76, s54, 0x100
	v_mov_b32_e32 v2, 0
	s_addc_u32 s77, s55, 0
	s_mov_b32 s54, 0
	v_mov_b32_e32 v3, v2
	v_mov_b32_e32 v4, v2
	v_mov_b32_e32 v5, v2
	v_mov_b32_e32 v6, v2
	v_mov_b32_e32 v7, v2
	v_mov_b32_e32 v8, v2
	v_mov_b32_e32 v9, v2
	v_mov_b32_e32 v18, v2
	v_mov_b32_e32 v19, v2
	v_mov_b32_e32 v20, v2
	v_mov_b32_e32 v21, v2
	v_mov_b32_e32 v22, v2
	v_mov_b32_e32 v23, v2
	v_mov_b32_e32 v24, v2
	v_mov_b32_e32 v25, v2
	v_mov_b32_e32 v34, v2
	v_mov_b32_e32 v35, v2
	v_mov_b32_e32 v36, v2
	v_mov_b32_e32 v37, v2
	v_mov_b32_e32 v38, v2
	v_mov_b32_e32 v39, v2
	v_mov_b32_e32 v40, v2
	v_mov_b32_e32 v41, v2
	v_mov_b32_e32 v50, v2
	v_mov_b32_e32 v51, v2
	v_mov_b32_e32 v52, v2
	v_mov_b32_e32 v53, v2
	v_mov_b32_e32 v54, v2
	v_mov_b32_e32 v55, v2
	v_mov_b32_e32 v56, v2
	v_mov_b32_e32 v57, v2
	v_mov_b32_e32 v10, v2
	v_mov_b32_e32 v11, v2
	v_mov_b32_e32 v12, v2
	v_mov_b32_e32 v13, v2
	v_mov_b32_e32 v14, v2
	v_mov_b32_e32 v15, v2
	v_mov_b32_e32 v16, v2
	v_mov_b32_e32 v17, v2
	v_mov_b32_e32 v26, v2
	v_mov_b32_e32 v27, v2
	v_mov_b32_e32 v28, v2
	v_mov_b32_e32 v29, v2
	v_mov_b32_e32 v30, v2
	v_mov_b32_e32 v31, v2
	v_mov_b32_e32 v32, v2
	v_mov_b32_e32 v33, v2
	v_mov_b32_e32 v42, v2
	v_mov_b32_e32 v43, v2
	v_mov_b32_e32 v44, v2
	v_mov_b32_e32 v45, v2
	v_mov_b32_e32 v46, v2
	v_mov_b32_e32 v47, v2
	v_mov_b32_e32 v48, v2
	v_mov_b32_e32 v49, v2
	v_mov_b32_e32 v58, v2
	v_mov_b32_e32 v59, v2
	v_mov_b32_e32 v60, v2
	v_mov_b32_e32 v61, v2
	v_mov_b32_e32 v62, v2
	v_mov_b32_e32 v63, v2
	v_mov_b32_e32 v64, v2
	v_mov_b32_e32 v65, v2
	v_mov_b32_e32 v66, v2
	v_mov_b32_e32 v67, v2
	v_mov_b32_e32 v68, v2
	v_mov_b32_e32 v69, v2
	v_mov_b32_e32 v70, v2
	v_mov_b32_e32 v71, v2
	v_mov_b32_e32 v72, v2
	v_mov_b32_e32 v73, v2
	v_mov_b32_e32 v82, v2
	v_mov_b32_e32 v83, v2
	v_mov_b32_e32 v84, v2
	v_mov_b32_e32 v85, v2
	v_mov_b32_e32 v86, v2
	v_mov_b32_e32 v87, v2
	v_mov_b32_e32 v88, v2
	v_mov_b32_e32 v89, v2
	v_mov_b32_e32 v98, v2
	v_mov_b32_e32 v99, v2
	v_mov_b32_e32 v100, v2
	v_mov_b32_e32 v101, v2
	v_mov_b32_e32 v102, v2
	v_mov_b32_e32 v103, v2
	v_mov_b32_e32 v104, v2
	v_mov_b32_e32 v105, v2
	v_mov_b32_e32 v114, v2
	v_mov_b32_e32 v115, v2
	v_mov_b32_e32 v116, v2
	v_mov_b32_e32 v117, v2
	v_mov_b32_e32 v118, v2
	v_mov_b32_e32 v119, v2
	v_mov_b32_e32 v120, v2
	v_mov_b32_e32 v121, v2
	v_mov_b32_e32 v74, v2
	v_mov_b32_e32 v75, v2
	v_mov_b32_e32 v76, v2
	v_mov_b32_e32 v77, v2
	v_mov_b32_e32 v78, v2
	v_mov_b32_e32 v79, v2
	v_mov_b32_e32 v80, v2
	v_mov_b32_e32 v81, v2
	v_mov_b32_e32 v90, v2
	v_mov_b32_e32 v91, v2
	v_mov_b32_e32 v92, v2
	v_mov_b32_e32 v93, v2
	v_mov_b32_e32 v94, v2
	v_mov_b32_e32 v95, v2
	v_mov_b32_e32 v96, v2
	v_mov_b32_e32 v97, v2
	v_mov_b32_e32 v106, v2
	v_mov_b32_e32 v107, v2
	v_mov_b32_e32 v108, v2
	v_mov_b32_e32 v109, v2
	v_mov_b32_e32 v110, v2
	v_mov_b32_e32 v111, v2
	v_mov_b32_e32 v112, v2
	v_mov_b32_e32 v113, v2
	v_mov_b32_e32 v122, v2
	v_mov_b32_e32 v123, v2
	v_mov_b32_e32 v124, v2
	v_mov_b32_e32 v125, v2
	v_mov_b32_e32 v126, v2
	v_mov_b32_e32 v127, v2
	v_mov_b32_e32 v128, v2
	v_mov_b32_e32 v129, v2
	.p2align	6

; template <class Epi, class Sched>
; __device__ __forceinline__ void gemm_phase(PG8_LAS unsigned char* lds, const Gemm g, const Sched& S, const Epi& E) {
;     ...
;         for (int t = 0; t < nt; t += 2) {
;             const bool last = (t == nt - 2);
;             const char* a1 = cA + (size_t)(t + 1) * kstep;
;             const char* a2 = last ? nA : cA + (size_t)(t + 2) * kstep; const char* b2 = last ? nB : cB + (size_t)(t + 2) * kstep;
;             const char* a3 = a2 + kstep; const char* b3 = b2 + kstep;
;     ...
; #pragma unroll
;         for (int a = 0; a < 2; ++a)
; #pragma unroll
;             for (int b = 0; b < 2; ++b)
; #pragma unroll
;                 for (int m = 0; m < 4; ++m)
; #pragma unroll
;                     for (int n = 0; n < 2; ++n) acc[a][b][m][n] = (f32x4){0.f, 0.f, 0.f, 0.f};
;         cur = nxt; cA = nA; cB = nB; ++ui;
.LBB0_1566:
	v_mov_b32_e32 v125, 0
	s_andn2_b64 vcc, exec, s[30:31]
	v_mov_b32_e32 v124, v125
	v_mov_b32_e32 v123, v125
	v_mov_b32_e32 v122, v125
	v_mov_b32_e32 v129, v125
	v_mov_b32_e32 v128, v125
	v_mov_b32_e32 v127, v125
	v_mov_b32_e32 v126, v125
	v_mov_b32_e32 v113, v125
	v_mov_b32_e32 v112, v125
	v_mov_b32_e32 v111, v125
	v_mov_b32_e32 v110, v125
	v_mov_b32_e32 v109, v125
	v_mov_b32_e32 v108, v125
	v_mov_b32_e32 v107, v125
	v_mov_b32_e32 v106, v125
	v_mov_b32_e32 v97, v125
	v_mov_b32_e32 v96, v125
	v_mov_b32_e32 v95, v125
	v_mov_b32_e32 v94, v125
	v_mov_b32_e32 v93, v125
	v_mov_b32_e32 v92, v125
	v_mov_b32_e32 v91, v125
	v_mov_b32_e32 v90, v125
	v_mov_b32_e32 v81, v125
	v_mov_b32_e32 v80, v125
	v_mov_b32_e32 v79, v125
	v_mov_b32_e32 v78, v125
	v_mov_b32_e32 v77, v125
	v_mov_b32_e32 v76, v125
	v_mov_b32_e32 v75, v125
	v_mov_b32_e32 v74, v125
	v_mov_b32_e32 v121, v125
	v_mov_b32_e32 v120, v125
	v_mov_b32_e32 v119, v125
	v_mov_b32_e32 v118, v125
	v_mov_b32_e32 v117, v125
	v_mov_b32_e32 v116, v125
	v_mov_b32_e32 v115, v125
	v_mov_b32_e32 v114, v125
	v_mov_b32_e32 v105, v125
	v_mov_b32_e32 v104, v125
	v_mov_b32_e32 v103, v125
	v_mov_b32_e32 v102, v125
	v_mov_b32_e32 v101, v125
	v_mov_b32_e32 v100, v125
	v_mov_b32_e32 v99, v125
	v_mov_b32_e32 v98, v125
	v_mov_b32_e32 v89, v125
	v_mov_b32_e32 v88, v125
	v_mov_b32_e32 v87, v125
	v_mov_b32_e32 v86, v125
	v_mov_b32_e32 v85, v125
	v_mov_b32_e32 v84, v125
	v_mov_b32_e32 v83, v125
	v_mov_b32_e32 v82, v125
	v_mov_b32_e32 v73, v125
	v_mov_b32_e32 v72, v125
	v_mov_b32_e32 v71, v125
	v_mov_b32_e32 v70, v125
	v_mov_b32_e32 v69, v125
	v_mov_b32_e32 v68, v125
	v_mov_b32_e32 v67, v125
	v_mov_b32_e32 v66, v125
	v_mov_b32_e32 v65, v125
	v_mov_b32_e32 v64, v125
	v_mov_b32_e32 v63, v125
	v_mov_b32_e32 v62, v125
	v_mov_b32_e32 v61, v125
	v_mov_b32_e32 v60, v125
	v_mov_b32_e32 v59, v125
	v_mov_b32_e32 v58, v125
	v_mov_b32_e32 v49, v125
	v_mov_b32_e32 v48, v125
	v_mov_b32_e32 v47, v125
	v_mov_b32_e32 v46, v125
	v_mov_b32_e32 v45, v125
	v_mov_b32_e32 v44, v125
	v_mov_b32_e32 v43, v125
	v_mov_b32_e32 v42, v125
	v_mov_b32_e32 v33, v125
	v_mov_b32_e32 v32, v125
	v_mov_b32_e32 v31, v125
	v_mov_b32_e32 v30, v125
	v_mov_b32_e32 v29, v125
	v_mov_b32_e32 v28, v125
	v_mov_b32_e32 v27, v125
	v_mov_b32_e32 v26, v125
	v_mov_b32_e32 v17, v125
	v_mov_b32_e32 v16, v125
	v_mov_b32_e32 v15, v125
	v_mov_b32_e32 v14, v125
	v_mov_b32_e32 v13, v125
	v_mov_b32_e32 v12, v125
	v_mov_b32_e32 v11, v125
	v_mov_b32_e32 v10, v125
	v_mov_b32_e32 v57, v125
	v_mov_b32_e32 v56, v125
	v_mov_b32_e32 v55, v125
	v_mov_b32_e32 v54, v125
	v_mov_b32_e32 v53, v125
	v_mov_b32_e32 v52, v125
	v_mov_b32_e32 v51, v125
	v_mov_b32_e32 v50, v125
	v_mov_b32_e32 v41, v125
	v_mov_b32_e32 v40, v125
	v_mov_b32_e32 v39, v125
	v_mov_b32_e32 v38, v125
	v_mov_b32_e32 v37, v125
	v_mov_b32_e32 v36, v125
	v_mov_b32_e32 v35, v125
	v_mov_b32_e32 v34, v125
	v_mov_b32_e32 v25, v125
	v_mov_b32_e32 v24, v125
	v_mov_b32_e32 v23, v125
	v_mov_b32_e32 v22, v125
	v_mov_b32_e32 v21, v125
	v_mov_b32_e32 v20, v125
	v_mov_b32_e32 v19, v125
	v_mov_b32_e32 v18, v125
	v_mov_b32_e32 v9, v125
	v_mov_b32_e32 v8, v125
	v_mov_b32_e32 v7, v125
	v_mov_b32_e32 v6, v125
	v_mov_b32_e32 v5, v125
	v_mov_b32_e32 v4, v125
	v_mov_b32_e32 v3, v125
	v_mov_b32_e32 v2, v125
	s_cbranch_vccnz .LBB0_1569
	s_add_u32 s44, s44, 0x80
	s_addc_u32 s45, s45, 0
	s_add_u32 s72, s50, 0x100
	v_mov_b32_e32 v2, 0
	s_addc_u32 s73, s51, 0
	s_mov_b32 s50, 0
	v_mov_b32_e32 v3, v2
	v_mov_b32_e32 v4, v2
	v_mov_b32_e32 v5, v2
	v_mov_b32_e32 v6, v2
	v_mov_b32_e32 v7, v2
	v_mov_b32_e32 v8, v2
	v_mov_b32_e32 v9, v2
	v_mov_b32_e32 v18, v2
	v_mov_b32_e32 v19, v2
	v_mov_b32_e32 v20, v2
	v_mov_b32_e32 v21, v2
	v_mov_b32_e32 v22, v2
	v_mov_b32_e32 v23, v2
	v_mov_b32_e32 v24, v2
	v_mov_b32_e32 v25, v2
	v_mov_b32_e32 v34, v2
	v_mov_b32_e32 v35, v2
	v_mov_b32_e32 v36, v2
	v_mov_b32_e32 v37, v2
	v_mov_b32_e32 v38, v2
	v_mov_b32_e32 v39, v2
	v_mov_b32_e32 v40, v2
	v_mov_b32_e32 v41, v2
	v_mov_b32_e32 v50, v2
	v_mov_b32_e32 v51, v2
	v_mov_b32_e32 v52, v2
	v_mov_b32_e32 v53, v2
	v_mov_b32_e32 v54, v2
	v_mov_b32_e32 v55, v2
	v_mov_b32_e32 v56, v2
	v_mov_b32_e32 v57, v2
	v_mov_b32_e32 v10, v2
	v_mov_b32_e32 v11, v2
	v_mov_b32_e32 v12, v2
	v_mov_b32_e32 v13, v2
	v_mov_b32_e32 v14, v2
	v_mov_b32_e32 v15, v2
	v_mov_b32_e32 v16, v2
	v_mov_b32_e32 v17, v2
	v_mov_b32_e32 v26, v2
	v_mov_b32_e32 v27, v2
	v_mov_b32_e32 v28, v2
	v_mov_b32_e32 v29, v2
	v_mov_b32_e32 v30, v2
	v_mov_b32_e32 v31, v2
	v_mov_b32_e32 v32, v2
	v_mov_b32_e32 v33, v2
	v_mov_b32_e32 v42, v2
	v_mov_b32_e32 v43, v2
	v_mov_b32_e32 v44, v2
	v_mov_b32_e32 v45, v2
	v_mov_b32_e32 v46, v2
	v_mov_b32_e32 v47, v2
	v_mov_b32_e32 v48, v2
	v_mov_b32_e32 v49, v2
	v_mov_b32_e32 v58, v2
	v_mov_b32_e32 v59, v2
	v_mov_b32_e32 v60, v2
	v_mov_b32_e32 v61, v2
	v_mov_b32_e32 v62, v2
	v_mov_b32_e32 v63, v2
	v_mov_b32_e32 v64, v2
	v_mov_b32_e32 v65, v2
	v_mov_b32_e32 v66, v2
	v_mov_b32_e32 v67, v2
	v_mov_b32_e32 v68, v2
	v_mov_b32_e32 v69, v2
	v_mov_b32_e32 v70, v2
	v_mov_b32_e32 v71, v2
	v_mov_b32_e32 v72, v2
	v_mov_b32_e32 v73, v2
	v_mov_b32_e32 v82, v2
	v_mov_b32_e32 v83, v2
	v_mov_b32_e32 v84, v2
	v_mov_b32_e32 v85, v2
	v_mov_b32_e32 v86, v2
	v_mov_b32_e32 v87, v2
	v_mov_b32_e32 v88, v2
	v_mov_b32_e32 v89, v2
	v_mov_b32_e32 v98, v2
	v_mov_b32_e32 v99, v2
	v_mov_b32_e32 v100, v2
	v_mov_b32_e32 v101, v2
	v_mov_b32_e32 v102, v2
	v_mov_b32_e32 v103, v2
	v_mov_b32_e32 v104, v2
	v_mov_b32_e32 v105, v2
	v_mov_b32_e32 v114, v2
	v_mov_b32_e32 v115, v2
	v_mov_b32_e32 v116, v2
	v_mov_b32_e32 v117, v2
	v_mov_b32_e32 v118, v2
	v_mov_b32_e32 v119, v2
	v_mov_b32_e32 v120, v2
	v_mov_b32_e32 v121, v2
	v_mov_b32_e32 v74, v2
	v_mov_b32_e32 v75, v2
	v_mov_b32_e32 v76, v2
	v_mov_b32_e32 v77, v2
	v_mov_b32_e32 v78, v2
	v_mov_b32_e32 v79, v2
	v_mov_b32_e32 v80, v2
	v_mov_b32_e32 v81, v2
	v_mov_b32_e32 v90, v2
	v_mov_b32_e32 v91, v2
	v_mov_b32_e32 v92, v2
	v_mov_b32_e32 v93, v2
	v_mov_b32_e32 v94, v2
	v_mov_b32_e32 v95, v2
	v_mov_b32_e32 v96, v2
	v_mov_b32_e32 v97, v2
	v_mov_b32_e32 v106, v2
	v_mov_b32_e32 v107, v2
	v_mov_b32_e32 v108, v2
	v_mov_b32_e32 v109, v2
	v_mov_b32_e32 v110, v2
	v_mov_b32_e32 v111, v2
	v_mov_b32_e32 v112, v2
	v_mov_b32_e32 v113, v2
	v_mov_b32_e32 v126, v2
	v_mov_b32_e32 v127, v2
	v_mov_b32_e32 v128, v2
	v_mov_b32_e32 v129, v2
	v_mov_b32_e32 v122, v2
	v_mov_b32_e32 v123, v2
	v_mov_b32_e32 v124, v2
	v_mov_b32_e32 v125, v2
	.p2align	6

;     __device__ bool next(int i, Unit& u) const { Unit s; if (!so.next(i / 3, s)) return false; u.pm = s.pm; u.pn = (i % 3) * 4 + s.pn; return true; }
; #define PG8_STAGE(bufoff, gbase, voff) do { _Pragma("unroll") for (int _i = 0; _i < 2; ++_i) \
;         __builtin_amdgcn_global_load_lds((const unsigned*)((const char*)(gbase) + (voff)[_i]), (PG8_LAS unsigned*)(lds + (bufoff) + ldsw + _i * 8192), 16, 0, 0); } while (0)
; #define PG8_WAIT_V(n) asm volatile("s_waitcnt vmcnt(" #n ")" ::: "memory")
; #define PG8_BAR __builtin_amdgcn_s_barrier()
; template <class Epi, class Sched>
; __device__ __forceinline__ void gemm_phase(PG8_LAS unsigned char* lds, const Gemm g, const Sched& S, const Epi& E) {
;     ...
;     f32x4 acc[2][2][4][2];
; #pragma unroll
;     for (int a = 0; a < 2; ++a)
; #pragma unroll
;         for (int b = 0; b < 2; ++b)
; #pragma unroll
;             for (int m = 0; m < 4; ++m)
; #pragma unroll
;                 for (int n = 0; n < 2; ++n) acc[a][b][m][n] = (f32x4){0.f, 0.f, 0.f, 0.f};
;     bf16x8 At[4][2], B0[2][2], B1[2][2];
;     const char* cA = (const char*)g.A + (size_t)cur.pm * tstepA; const char* cB = (const char*)g.Bt + (size_t)cur.pn * tstepB;
;     PG8_STAGE(PG8_SB(0, 0), cB, voffB); PG8_STAGE(PG8_SB(0, 1), cB + hstepB, voffB); PG8_STAGE(PG8_SA(0, 0), cA, voffA); PG8_STAGE(PG8_SA(0, 1), cA + hstepA, voffA);
;     if (wr == 1) PG8_BAR;
;     PG8_WAIT_V(2); PG8_BAR;
;     PG8_STAGE(PG8_SB(1, 0), cB + kstep, voffB); PG8_STAGE(PG8_SA(1, 0), cA + kstep, voffA); PG8_STAGE(PG8_SB(1, 1), cB + hstepB + kstep, voffB);
;     PG8_WAIT_V(6); PG8_BAR;
;     for (;;) {
;         const bool has_next = S.next(ui + 1, nxt);
;         const char* nA = has_next ? (const char*)g.A + (size_t)nxt.pm * tstepA : cA; const char* nB = has_next ? (const char*)g.Bt + (size_t)nxt.pn * tstepB : cB;
;         for (int t = 0; t < nt; t += 2) {
;             const bool last = (t == nt - 2);
;             const char* a1 = cA + (size_t)(t + 1) * kstep;
;             const char* a2 = last ? nA : cA + (size_t)(t + 2) * kstep; const char* b2 = last ? nB : cB + (size_t)(t + 2) * kstep;
;             const char* a3 = a2 + kstep; const char* b3 = b2 + kstep;
.LBB0_1645:
	v_mov_b32_e32 v125, 0
	s_andn2_b64 vcc, exec, s[42:43]
	v_mov_b32_e32 v124, v125
	v_mov_b32_e32 v123, v125
	v_mov_b32_e32 v122, v125
	v_mov_b32_e32 v129, v125
	v_mov_b32_e32 v128, v125
	v_mov_b32_e32 v127, v125
	v_mov_b32_e32 v126, v125
	v_mov_b32_e32 v113, v125
	v_mov_b32_e32 v112, v125
	v_mov_b32_e32 v111, v125
	v_mov_b32_e32 v110, v125
	v_mov_b32_e32 v109, v125
	v_mov_b32_e32 v108, v125
	v_mov_b32_e32 v107, v125
	v_mov_b32_e32 v106, v125
	v_mov_b32_e32 v97, v125
	v_mov_b32_e32 v96, v125
	v_mov_b32_e32 v95, v125
	v_mov_b32_e32 v94, v125
	v_mov_b32_e32 v93, v125
	v_mov_b32_e32 v92, v125
	v_mov_b32_e32 v91, v125
	v_mov_b32_e32 v90, v125
	v_mov_b32_e32 v81, v125
	v_mov_b32_e32 v80, v125
	v_mov_b32_e32 v79, v125
	v_mov_b32_e32 v78, v125
	v_mov_b32_e32 v77, v125
	v_mov_b32_e32 v76, v125
	v_mov_b32_e32 v75, v125
	v_mov_b32_e32 v74, v125
	v_mov_b32_e32 v121, v125
	v_mov_b32_e32 v120, v125
	v_mov_b32_e32 v119, v125
	v_mov_b32_e32 v118, v125
	v_mov_b32_e32 v117, v125
	v_mov_b32_e32 v116, v125
	v_mov_b32_e32 v115, v125
	v_mov_b32_e32 v114, v125
	v_mov_b32_e32 v105, v125
	v_mov_b32_e32 v104, v125
	v_mov_b32_e32 v103, v125
	v_mov_b32_e32 v102, v125
	v_mov_b32_e32 v101, v125
	v_mov_b32_e32 v100, v125
	v_mov_b32_e32 v99, v125
	v_mov_b32_e32 v98, v125
	v_mov_b32_e32 v89, v125
	v_mov_b32_e32 v88, v125
	v_mov_b32_e32 v87, v125
	v_mov_b32_e32 v86, v125
	v_mov_b32_e32 v85, v125
	v_mov_b32_e32 v84, v125
	v_mov_b32_e32 v83, v125
	v_mov_b32_e32 v82, v125
	v_mov_b32_e32 v73, v125
	v_mov_b32_e32 v72, v125
	v_mov_b32_e32 v71, v125
	v_mov_b32_e32 v70, v125
	v_mov_b32_e32 v69, v125
	v_mov_b32_e32 v68, v125
	v_mov_b32_e32 v67, v125
	v_mov_b32_e32 v66, v125
	v_mov_b32_e32 v65, v125
	v_mov_b32_e32 v64, v125
	v_mov_b32_e32 v63, v125
	v_mov_b32_e32 v62, v125
	v_mov_b32_e32 v61, v125
	v_mov_b32_e32 v60, v125
	v_mov_b32_e32 v59, v125
	v_mov_b32_e32 v58, v125
	v_mov_b32_e32 v49, v125
	v_mov_b32_e32 v48, v125
	v_mov_b32_e32 v47, v125
	v_mov_b32_e32 v46, v125
	v_mov_b32_e32 v45, v125
	v_mov_b32_e32 v44, v125
	v_mov_b32_e32 v43, v125
	v_mov_b32_e32 v42, v125
	v_mov_b32_e32 v33, v125
	v_mov_b32_e32 v32, v125
	v_mov_b32_e32 v31, v125
	v_mov_b32_e32 v30, v125
	v_mov_b32_e32 v29, v125
	v_mov_b32_e32 v28, v125
	v_mov_b32_e32 v27, v125
	v_mov_b32_e32 v26, v125
	v_mov_b32_e32 v17, v125
	v_mov_b32_e32 v16, v125
	v_mov_b32_e32 v15, v125
	v_mov_b32_e32 v14, v125
	v_mov_b32_e32 v13, v125
	v_mov_b32_e32 v12, v125
	v_mov_b32_e32 v11, v125
	v_mov_b32_e32 v10, v125
	v_mov_b32_e32 v57, v125
	v_mov_b32_e32 v56, v125
	v_mov_b32_e32 v55, v125
	v_mov_b32_e32 v54, v125
	v_mov_b32_e32 v53, v125
	v_mov_b32_e32 v52, v125
	v_mov_b32_e32 v51, v125
	v_mov_b32_e32 v50, v125
	v_mov_b32_e32 v41, v125
	v_mov_b32_e32 v40, v125
	v_mov_b32_e32 v39, v125
	v_mov_b32_e32 v38, v125
	v_mov_b32_e32 v37, v125
	v_mov_b32_e32 v36, v125
	v_mov_b32_e32 v35, v125
	v_mov_b32_e32 v34, v125
	v_mov_b32_e32 v25, v125
	v_mov_b32_e32 v24, v125
	v_mov_b32_e32 v23, v125
	v_mov_b32_e32 v22, v125
	v_mov_b32_e32 v21, v125
	v_mov_b32_e32 v20, v125
	v_mov_b32_e32 v19, v125
	v_mov_b32_e32 v18, v125
	v_mov_b32_e32 v9, v125
	v_mov_b32_e32 v8, v125
	v_mov_b32_e32 v7, v125
	v_mov_b32_e32 v6, v125
	v_mov_b32_e32 v5, v125
	v_mov_b32_e32 v4, v125
	s_waitcnt lgkmcnt(0)
	v_mov_b32_e32 v3, v125
	v_mov_b32_e32 v2, v125
	s_cbranch_vccnz .LBB0_1648
	s_add_u32 s54, s54, 0x80
	s_addc_u32 s55, s55, 0
	s_add_u32 s78, s56, 0x100
	v_mov_b32_e32 v2, 0
	s_addc_u32 s79, s57, 0
	s_mov_b32 s56, 0
	v_mov_b32_e32 v3, v2
	v_mov_b32_e32 v4, v2
	v_mov_b32_e32 v5, v2
	v_mov_b32_e32 v6, v2
	v_mov_b32_e32 v7, v2
	v_mov_b32_e32 v8, v2
	v_mov_b32_e32 v9, v2
	v_mov_b32_e32 v18, v2
	v_mov_b32_e32 v19, v2
	v_mov_b32_e32 v20, v2
	v_mov_b32_e32 v21, v2
	v_mov_b32_e32 v22, v2
	v_mov_b32_e32 v23, v2
	v_mov_b32_e32 v24, v2
	v_mov_b32_e32 v25, v2
	v_mov_b32_e32 v34, v2
	v_mov_b32_e32 v35, v2
	v_mov_b32_e32 v36, v2
	v_mov_b32_e32 v37, v2
	v_mov_b32_e32 v38, v2
	v_mov_b32_e32 v39, v2
	v_mov_b32_e32 v40, v2
	v_mov_b32_e32 v41, v2
	v_mov_b32_e32 v50, v2
	v_mov_b32_e32 v51, v2
	v_mov_b32_e32 v52, v2
	v_mov_b32_e32 v53, v2
	v_mov_b32_e32 v54, v2
	v_mov_b32_e32 v55, v2
	v_mov_b32_e32 v56, v2
	v_mov_b32_e32 v57, v2
	v_mov_b32_e32 v10, v2
	v_mov_b32_e32 v11, v2
	v_mov_b32_e32 v12, v2
	v_mov_b32_e32 v13, v2
	v_mov_b32_e32 v14, v2
	v_mov_b32_e32 v15, v2
	v_mov_b32_e32 v16, v2
	v_mov_b32_e32 v17, v2
	v_mov_b32_e32 v26, v2
	v_mov_b32_e32 v27, v2
	v_mov_b32_e32 v28, v2
	v_mov_b32_e32 v29, v2
	v_mov_b32_e32 v30, v2
	v_mov_b32_e32 v31, v2
	v_mov_b32_e32 v32, v2
	v_mov_b32_e32 v33, v2
	v_mov_b32_e32 v42, v2
	v_mov_b32_e32 v43, v2
	v_mov_b32_e32 v44, v2
	v_mov_b32_e32 v45, v2
	v_mov_b32_e32 v46, v2
	v_mov_b32_e32 v47, v2
	v_mov_b32_e32 v48, v2
	v_mov_b32_e32 v49, v2
	v_mov_b32_e32 v58, v2
	v_mov_b32_e32 v59, v2
	v_mov_b32_e32 v60, v2
	v_mov_b32_e32 v61, v2
	v_mov_b32_e32 v62, v2
	v_mov_b32_e32 v63, v2
	v_mov_b32_e32 v64, v2
	v_mov_b32_e32 v65, v2
	v_mov_b32_e32 v66, v2
	v_mov_b32_e32 v67, v2
	v_mov_b32_e32 v68, v2
	v_mov_b32_e32 v69, v2
	v_mov_b32_e32 v70, v2
	v_mov_b32_e32 v71, v2
	v_mov_b32_e32 v72, v2
	v_mov_b32_e32 v73, v2
	v_mov_b32_e32 v82, v2
	v_mov_b32_e32 v83, v2
	v_mov_b32_e32 v84, v2
	v_mov_b32_e32 v85, v2
	v_mov_b32_e32 v86, v2
	v_mov_b32_e32 v87, v2
	v_mov_b32_e32 v88, v2
	v_mov_b32_e32 v89, v2
	v_mov_b32_e32 v98, v2
	v_mov_b32_e32 v99, v2
	v_mov_b32_e32 v100, v2
	v_mov_b32_e32 v101, v2
	v_mov_b32_e32 v102, v2
	v_mov_b32_e32 v103, v2
	v_mov_b32_e32 v104, v2
	v_mov_b32_e32 v105, v2
	v_mov_b32_e32 v114, v2
	v_mov_b32_e32 v115, v2
	v_mov_b32_e32 v116, v2
	v_mov_b32_e32 v117, v2
	v_mov_b32_e32 v118, v2
	v_mov_b32_e32 v119, v2
	v_mov_b32_e32 v120, v2
	v_mov_b32_e32 v121, v2
	v_mov_b32_e32 v74, v2
	v_mov_b32_e32 v75, v2
	v_mov_b32_e32 v76, v2
	v_mov_b32_e32 v77, v2
	v_mov_b32_e32 v78, v2
	v_mov_b32_e32 v79, v2
	v_mov_b32_e32 v80, v2
	v_mov_b32_e32 v81, v2
	v_mov_b32_e32 v90, v2
	v_mov_b32_e32 v91, v2
	v_mov_b32_e32 v92, v2
	v_mov_b32_e32 v93, v2
	v_mov_b32_e32 v94, v2
	v_mov_b32_e32 v95, v2
	v_mov_b32_e32 v96, v2
	v_mov_b32_e32 v97, v2
	v_mov_b32_e32 v106, v2
	v_mov_b32_e32 v107, v2
	v_mov_b32_e32 v108, v2
	v_mov_b32_e32 v109, v2
	v_mov_b32_e32 v110, v2
	v_mov_b32_e32 v111, v2
	v_mov_b32_e32 v112, v2
	v_mov_b32_e32 v113, v2
	v_mov_b32_e32 v126, v2
	v_mov_b32_e32 v127, v2
	v_mov_b32_e32 v128, v2
	v_mov_b32_e32 v129, v2
	v_mov_b32_e32 v122, v2
	v_mov_b32_e32 v123, v2
	v_mov_b32_e32 v124, v2
	v_mov_b32_e32 v125, v2
	.p2align	6
